# K-loops: priority raised before the barrier that opens each MFMA block (redundant lgkmcnt(0) behind it dropped), lowered after the closing barrier; plus batched census loads and alternating gMLP item
# speedup vs baseline: 1.0130x; 1.0130x over previous
.LBB0_111:
	s_add_u32 s72, vcc_lo, 0xffea0080
	s_addc_u32 s73, vcc_hi, -1
	s_add_i32 s95, 0, 0x10000
	s_cmp_eq_u32 s93, 12
	s_cselect_b32 s79, s1, s73
	s_cselect_b32 s78, s0, s72
	v_add_u32_e32 v26, s95, v186
	s_cselect_b32 s77, s89, s85
	s_cselect_b32 s76, s88, s84
	s_add_i32 s12, 0, 0x14000
	ds_read_b128 v[36:39], v26
	ds_read_b128 v[56:59], v26 offset:1024
	ds_read_b128 v[84:87], v26 offset:2048
	ds_read_b128 v[104:107], v26 offset:3072
	v_add_u32_e32 v26, s12, v186
	ds_read_b128 v[124:127], v26
	ds_read_b128 v[144:147], v26 offset:1024
	ds_read_b128 v[156:159], v26 offset:2048
	ds_read_b128 v[180:183], v26 offset:3072
	v_lshl_add_u64 v[226:227], vcc, 0, v[176:177]
	s_add_i32 m0, s17, 0xc000
	ds_read_b128 v[190:193], v188
	ds_read_b128 v[194:197], v188 offset:1024
	ds_read_b128 v[198:201], v188 offset:2048
	ds_read_b128 v[202:205], v188 offset:3072
	ds_read_b128 v[206:209], v188 offset:4096
	ds_read_b128 v[210:213], v188 offset:5120
	ds_read_b128 v[214:217], v188 offset:6144
	ds_read_b128 v[218:221], v188 offset:7168
	global_load_lds_dwordx4 v[226:227], off
	v_lshl_add_u64 v[226:227], vcc, 0, v[178:179]
	s_add_i32 m0, s17, 0xe000
	s_nop 0
	global_load_lds_dwordx4 v[226:227], off
	s_waitcnt vmcnt(8)
	s_waitcnt lgkmcnt(0)
	s_setprio 1
	s_barrier
	v_mfma_f32_16x16x32_bf16 v[148:151], v[36:39], v[190:193], v[148:151]
	v_mfma_f32_16x16x32_bf16 v[152:155], v[84:87], v[190:193], v[152:155]
	v_mfma_f32_16x16x32_bf16 v[128:131], v[36:39], v[198:201], v[128:131]
	v_mfma_f32_16x16x32_bf16 v[132:135], v[84:87], v[198:201], v[132:135]
	v_mfma_f32_16x16x32_bf16 v[108:111], v[36:39], v[206:209], v[108:111]
	v_mfma_f32_16x16x32_bf16 v[112:115], v[84:87], v[206:209], v[112:115]
	v_mfma_f32_16x16x32_bf16 v[88:91], v[36:39], v[214:217], v[88:91]
	v_mfma_f32_16x16x32_bf16 v[92:95], v[84:87], v[214:217], v[92:95]
	v_mfma_f32_16x16x32_bf16 v[148:151], v[56:59], v[194:197], v[148:151]
	v_mfma_f32_16x16x32_bf16 v[152:155], v[104:107], v[194:197], v[152:155]
	v_mfma_f32_16x16x32_bf16 v[128:131], v[56:59], v[202:205], v[128:131]
	v_mfma_f32_16x16x32_bf16 v[132:135], v[104:107], v[202:205], v[132:135]
	v_mfma_f32_16x16x32_bf16 v[108:111], v[56:59], v[210:213], v[108:111]
	v_mfma_f32_16x16x32_bf16 v[112:115], v[104:107], v[210:213], v[112:115]
	v_mfma_f32_16x16x32_bf16 v[88:91], v[56:59], v[218:221], v[88:91]
	v_mfma_f32_16x16x32_bf16 v[92:95], v[104:107], v[218:221], v[92:95]
	s_setprio 0
	s_setprio 1
	v_mfma_f32_16x16x32_bf16 v[140:143], v[124:127], v[190:193], v[140:143]
	v_mfma_f32_16x16x32_bf16 v[136:139], v[156:159], v[190:193], v[136:139]
	v_mfma_f32_16x16x32_bf16 v[120:123], v[124:127], v[198:201], v[120:123]
	v_mfma_f32_16x16x32_bf16 v[116:119], v[156:159], v[198:201], v[116:119]
	v_mfma_f32_16x16x32_bf16 v[100:103], v[124:127], v[206:209], v[100:103]
	v_mfma_f32_16x16x32_bf16 v[96:99], v[156:159], v[206:209], v[96:99]
	v_mfma_f32_16x16x32_bf16 v[80:83], v[124:127], v[214:217], v[80:83]
	v_mfma_f32_16x16x32_bf16 v[76:79], v[156:159], v[214:217], v[76:79]
	v_mfma_f32_16x16x32_bf16 v[140:143], v[144:147], v[194:197], v[140:143]
	v_mfma_f32_16x16x32_bf16 v[136:139], v[180:183], v[194:197], v[136:139]
	v_mfma_f32_16x16x32_bf16 v[120:123], v[144:147], v[202:205], v[120:123]
	v_mfma_f32_16x16x32_bf16 v[116:119], v[180:183], v[202:205], v[116:119]
	v_mfma_f32_16x16x32_bf16 v[100:103], v[144:147], v[210:213], v[100:103]
	v_mfma_f32_16x16x32_bf16 v[96:99], v[180:183], v[210:213], v[96:99]
	v_mfma_f32_16x16x32_bf16 v[80:83], v[144:147], v[218:221], v[80:83]
	v_mfma_f32_16x16x32_bf16 v[76:79], v[180:183], v[218:221], v[76:79]
	s_barrier
	s_setprio 0
	s_add_i32 s72, s95, s16
	v_lshl_add_u64 v[226:227], s[76:77], 0, v[164:165]
	s_mov_b32 m0, s72
	ds_read_b128 v[190:193], v188 offset:16384
	ds_read_b128 v[194:197], v188 offset:17408
	ds_read_b128 v[198:201], v188 offset:18432
	ds_read_b128 v[202:205], v188 offset:19456
	ds_read_b128 v[206:209], v188 offset:20480
	ds_read_b128 v[210:213], v188 offset:21504
	ds_read_b128 v[214:217], v188 offset:22528
	ds_read_b128 v[218:221], v188 offset:23552
	global_load_lds_dwordx4 v[226:227], off
	s_add_i32 m0, s72, 0x2000
	s_add_u32 s72, s76, 0x40000
	v_lshl_add_u64 v[228:229], s[76:77], 0, v[160:161]
	s_addc_u32 s73, s77, 0
	s_add_i32 s12, s12, s16
	global_load_lds_dwordx4 v[228:229], off
	v_lshl_add_u64 v[230:231], s[72:73], 0, v[164:165]
	s_mov_b32 m0, s12
	v_lshl_add_u64 v[232:233], s[78:79], 0, v[162:163]
	global_load_lds_dwordx4 v[230:231], off
	v_lshl_add_u64 v[230:231], s[72:73], 0, v[160:161]
	s_add_i32 m0, s12, 0x2000
	s_nop 0
	global_load_lds_dwordx4 v[230:231], off
	v_lshl_add_u64 v[230:231], s[78:79], 0, v[166:167]
	s_mov_b32 m0, s17
	s_nop 0
	global_load_lds_dwordx4 v[230:231], off
	s_mov_b32 m0, s46
	s_nop 0
	global_load_lds_dwordx4 v[232:233], off
	s_waitcnt vmcnt(8)
	s_waitcnt lgkmcnt(0)
	s_setprio 1
	s_barrier
	v_mfma_f32_16x16x32_bf16 v[68:71], v[36:39], v[190:193], v[68:71]
	v_mfma_f32_16x16x32_bf16 v[72:75], v[84:87], v[190:193], v[72:75]
	v_mfma_f32_16x16x32_bf16 v[48:51], v[36:39], v[198:201], v[48:51]
	v_mfma_f32_16x16x32_bf16 v[52:55], v[84:87], v[198:201], v[52:55]
	v_mfma_f32_16x16x32_bf16 v[28:31], v[36:39], v[206:209], v[28:31]
	v_mfma_f32_16x16x32_bf16 v[32:35], v[84:87], v[206:209], v[32:35]
	v_mfma_f32_16x16x32_bf16 v[10:13], v[36:39], v[214:217], v[10:13]
	v_mfma_f32_16x16x32_bf16 v[14:17], v[84:87], v[214:217], v[14:17]
	v_mfma_f32_16x16x32_bf16 v[68:71], v[56:59], v[194:197], v[68:71]
	v_mfma_f32_16x16x32_bf16 v[72:75], v[104:107], v[194:197], v[72:75]
	v_mfma_f32_16x16x32_bf16 v[48:51], v[56:59], v[202:205], v[48:51]
	v_mfma_f32_16x16x32_bf16 v[52:55], v[104:107], v[202:205], v[52:55]
	v_mfma_f32_16x16x32_bf16 v[28:31], v[56:59], v[210:213], v[28:31]
	v_mfma_f32_16x16x32_bf16 v[32:35], v[104:107], v[210:213], v[32:35]
	v_mfma_f32_16x16x32_bf16 v[10:13], v[56:59], v[218:221], v[10:13]
	v_mfma_f32_16x16x32_bf16 v[14:17], v[104:107], v[218:221], v[14:17]
	s_setprio 0
	s_setprio 1
	v_mfma_f32_16x16x32_bf16 v[44:47], v[124:127], v[198:201], v[44:47]
	v_mfma_f32_16x16x32_bf16 v[40:43], v[156:159], v[198:201], v[40:43]
	v_mfma_f32_16x16x32_bf16 v[22:25], v[124:127], v[206:209], v[22:25]
	v_mfma_f32_16x16x32_bf16 v[18:21], v[156:159], v[206:209], v[18:21]
	v_mfma_f32_16x16x32_bf16 v[2:5], v[124:127], v[214:217], v[2:5]
	v_mfma_f32_16x16x32_bf16 v[6:9], v[156:159], v[214:217], v[6:9]
	v_mfma_f32_16x16x32_bf16 v[36:39], v[124:127], v[190:193], v[64:67]
	v_mfma_f32_16x16x32_bf16 v[56:59], v[156:159], v[190:193], v[60:63]
	v_mfma_f32_16x16x32_bf16 v[44:47], v[144:147], v[202:205], v[44:47]
	v_mfma_f32_16x16x32_bf16 v[40:43], v[180:183], v[202:205], v[40:43]
	v_mfma_f32_16x16x32_bf16 v[22:25], v[144:147], v[210:213], v[22:25]
	v_mfma_f32_16x16x32_bf16 v[18:21], v[180:183], v[210:213], v[18:21]
	v_mfma_f32_16x16x32_bf16 v[2:5], v[144:147], v[218:221], v[2:5]
	v_mfma_f32_16x16x32_bf16 v[6:9], v[180:183], v[218:221], v[6:9]
	v_mfma_f32_16x16x32_bf16 v[36:39], v[144:147], v[194:197], v[36:39]
	v_mfma_f32_16x16x32_bf16 v[56:59], v[180:183], v[194:197], v[56:59]
	s_barrier
	s_setprio 0
	s_add_i32 s12, 0, 0x18000
	v_add_u32_e32 v26, s12, v186
	s_add_i32 s95, 0, 0x1c000
	ds_read_b128 v[60:63], v26
	ds_read_b128 v[64:67], v26 offset:1024
	ds_read_b128 v[84:87], v26 offset:2048
	ds_read_b128 v[104:107], v26 offset:3072
	v_add_u32_e32 v26, s95, v186
	ds_read_b128 v[124:127], v26
	ds_read_b128 v[144:147], v26 offset:1024
	ds_read_b128 v[156:159], v26 offset:2048
	ds_read_b128 v[180:183], v26 offset:3072
	s_add_u32 s72, s78, 0x160000
	s_addc_u32 s73, s79, 0
	s_mov_b32 m0, s47
	v_lshl_add_u64 v[234:235], s[72:73], 0, v[166:167]
	ds_read_b128 v[190:193], v188 offset:32768
	ds_read_b128 v[194:197], v188 offset:33792
	ds_read_b128 v[198:201], v188 offset:34816
	ds_read_b128 v[202:205], v188 offset:35840
	ds_read_b128 v[206:209], v188 offset:36864
	ds_read_b128 v[210:213], v188 offset:37888
	ds_read_b128 v[214:217], v188 offset:38912
	ds_read_b128 v[218:221], v188 offset:39936
	global_load_lds_dwordx4 v[234:235], off
	v_lshl_add_u64 v[234:235], s[72:73], 0, v[162:163]
	s_mov_b32 m0, s8
	s_nop 0
	global_load_lds_dwordx4 v[234:235], off
	s_waitcnt vmcnt(8)
	s_waitcnt lgkmcnt(0)
	s_setprio 1
	s_barrier
	v_mfma_f32_16x16x32_bf16 v[148:151], v[60:63], v[190:193], v[148:151]
	v_mfma_f32_16x16x32_bf16 v[152:155], v[84:87], v[190:193], v[152:155]
	v_mfma_f32_16x16x32_bf16 v[128:131], v[60:63], v[198:201], v[128:131]
	v_mfma_f32_16x16x32_bf16 v[132:135], v[84:87], v[198:201], v[132:135]
	v_mfma_f32_16x16x32_bf16 v[108:111], v[60:63], v[206:209], v[108:111]
	v_mfma_f32_16x16x32_bf16 v[112:115], v[84:87], v[206:209], v[112:115]
	v_mfma_f32_16x16x32_bf16 v[88:91], v[60:63], v[214:217], v[88:91]
	v_mfma_f32_16x16x32_bf16 v[92:95], v[84:87], v[214:217], v[92:95]
	v_mfma_f32_16x16x32_bf16 v[148:151], v[64:67], v[194:197], v[148:151]
	v_mfma_f32_16x16x32_bf16 v[152:155], v[104:107], v[194:197], v[152:155]
	v_mfma_f32_16x16x32_bf16 v[128:131], v[64:67], v[202:205], v[128:131]
	v_mfma_f32_16x16x32_bf16 v[132:135], v[104:107], v[202:205], v[132:135]
	v_mfma_f32_16x16x32_bf16 v[108:111], v[64:67], v[210:213], v[108:111]
	v_mfma_f32_16x16x32_bf16 v[112:115], v[104:107], v[210:213], v[112:115]
	v_mfma_f32_16x16x32_bf16 v[88:91], v[64:67], v[218:221], v[88:91]
	v_mfma_f32_16x16x32_bf16 v[92:95], v[104:107], v[218:221], v[92:95]
	s_setprio 0
	s_setprio 1
	v_mfma_f32_16x16x32_bf16 v[140:143], v[124:127], v[190:193], v[140:143]
	v_mfma_f32_16x16x32_bf16 v[136:139], v[156:159], v[190:193], v[136:139]
	v_mfma_f32_16x16x32_bf16 v[120:123], v[124:127], v[198:201], v[120:123]
	v_mfma_f32_16x16x32_bf16 v[116:119], v[156:159], v[198:201], v[116:119]
	v_mfma_f32_16x16x32_bf16 v[100:103], v[124:127], v[206:209], v[100:103]
	v_mfma_f32_16x16x32_bf16 v[96:99], v[156:159], v[206:209], v[96:99]
	v_mfma_f32_16x16x32_bf16 v[80:83], v[124:127], v[214:217], v[80:83]
	v_mfma_f32_16x16x32_bf16 v[76:79], v[156:159], v[214:217], v[76:79]
	v_mfma_f32_16x16x32_bf16 v[140:143], v[144:147], v[194:197], v[140:143]
	v_mfma_f32_16x16x32_bf16 v[136:139], v[180:183], v[194:197], v[136:139]
	v_mfma_f32_16x16x32_bf16 v[120:123], v[144:147], v[202:205], v[120:123]
	v_mfma_f32_16x16x32_bf16 v[116:119], v[180:183], v[202:205], v[116:119]
	v_mfma_f32_16x16x32_bf16 v[100:103], v[144:147], v[210:213], v[100:103]
	v_mfma_f32_16x16x32_bf16 v[96:99], v[180:183], v[210:213], v[96:99]
	v_mfma_f32_16x16x32_bf16 v[80:83], v[144:147], v[218:221], v[80:83]
	v_mfma_f32_16x16x32_bf16 v[76:79], v[180:183], v[218:221], v[76:79]
	s_barrier
	s_setprio 0
	s_add_i32 s12, s12, s16
	v_lshl_add_u64 v[226:227], v[226:227], 0, s[82:83]
	s_mov_b32 m0, s12
	ds_read_b128 v[190:193], v188 offset:49152
	ds_read_b128 v[194:197], v188 offset:50176
	ds_read_b128 v[198:201], v188 offset:51200
	ds_read_b128 v[202:205], v188 offset:52224
	ds_read_b128 v[206:209], v188 offset:53248
	ds_read_b128 v[210:213], v188 offset:54272
	ds_read_b128 v[214:217], v188 offset:55296
	ds_read_b128 v[218:221], v188 offset:56320
	global_load_lds_dwordx4 v[226:227], off
	s_add_i32 m0, s12, 0x2000
	s_add_u32 s72, s76, 0x40080
	v_lshl_add_u64 v[226:227], v[228:229], 0, s[82:83]
	s_addc_u32 s73, s77, 0
	s_add_i32 s12, s95, s16
	global_load_lds_dwordx4 v[226:227], off
	v_lshl_add_u64 v[226:227], s[72:73], 0, v[164:165]
	s_mov_b32 m0, s12
	s_nop 0
	global_load_lds_dwordx4 v[226:227], off
	v_lshl_add_u64 v[226:227], s[72:73], 0, v[160:161]
	s_add_i32 m0, s12, 0x2000
	s_nop 0
	global_load_lds_dwordx4 v[226:227], off
	v_lshl_add_u64 v[226:227], v[230:231], 0, s[82:83]
	s_mov_b32 m0, s22
	s_nop 0
	global_load_lds_dwordx4 v[226:227], off
	v_lshl_add_u64 v[226:227], v[232:233], 0, s[82:83]
	s_mov_b32 m0, s80
	s_nop 0
	global_load_lds_dwordx4 v[226:227], off
	s_waitcnt vmcnt(8)
	s_waitcnt lgkmcnt(0)
	s_setprio 1
	s_barrier
	v_mfma_f32_16x16x32_bf16 v[68:71], v[60:63], v[190:193], v[68:71]
	v_mfma_f32_16x16x32_bf16 v[72:75], v[84:87], v[190:193], v[72:75]
	v_mfma_f32_16x16x32_bf16 v[48:51], v[60:63], v[198:201], v[48:51]
	v_mfma_f32_16x16x32_bf16 v[52:55], v[84:87], v[198:201], v[52:55]
	v_mfma_f32_16x16x32_bf16 v[28:31], v[60:63], v[206:209], v[28:31]
	v_mfma_f32_16x16x32_bf16 v[32:35], v[84:87], v[206:209], v[32:35]
	v_mfma_f32_16x16x32_bf16 v[10:13], v[60:63], v[214:217], v[10:13]
	v_mfma_f32_16x16x32_bf16 v[14:17], v[84:87], v[214:217], v[14:17]
	v_mfma_f32_16x16x32_bf16 v[68:71], v[64:67], v[194:197], v[68:71]
	v_mfma_f32_16x16x32_bf16 v[72:75], v[104:107], v[194:197], v[72:75]
	v_mfma_f32_16x16x32_bf16 v[48:51], v[64:67], v[202:205], v[48:51]
	v_mfma_f32_16x16x32_bf16 v[52:55], v[104:107], v[202:205], v[52:55]
	v_mfma_f32_16x16x32_bf16 v[28:31], v[64:67], v[210:213], v[28:31]
	v_mfma_f32_16x16x32_bf16 v[32:35], v[104:107], v[210:213], v[32:35]
	v_mfma_f32_16x16x32_bf16 v[10:13], v[64:67], v[218:221], v[10:13]
	v_mfma_f32_16x16x32_bf16 v[14:17], v[104:107], v[218:221], v[14:17]
	s_setprio 0
	s_setprio 1
	v_mfma_f32_16x16x32_bf16 v[36:39], v[124:127], v[190:193], v[36:39]
	v_mfma_f32_16x16x32_bf16 v[64:67], v[144:147], v[194:197], v[36:39]
	v_mfma_f32_16x16x32_bf16 v[36:39], v[156:159], v[190:193], v[56:59]
	v_mfma_f32_16x16x32_bf16 v[60:63], v[180:183], v[194:197], v[36:39]
	v_mfma_f32_16x16x32_bf16 v[36:39], v[124:127], v[198:201], v[44:47]
	v_mfma_f32_16x16x32_bf16 v[44:47], v[144:147], v[202:205], v[36:39]
	v_mfma_f32_16x16x32_bf16 v[36:39], v[156:159], v[198:201], v[40:43]
	v_mfma_f32_16x16x32_bf16 v[22:25], v[124:127], v[206:209], v[22:25]
	v_mfma_f32_16x16x32_bf16 v[18:21], v[156:159], v[206:209], v[18:21]
	v_mfma_f32_16x16x32_bf16 v[2:5], v[124:127], v[214:217], v[2:5]
	v_mfma_f32_16x16x32_bf16 v[6:9], v[156:159], v[214:217], v[6:9]
	v_mfma_f32_16x16x32_bf16 v[40:43], v[180:183], v[202:205], v[36:39]
	v_mfma_f32_16x16x32_bf16 v[22:25], v[144:147], v[210:213], v[22:25]
	v_mfma_f32_16x16x32_bf16 v[18:21], v[180:183], v[210:213], v[18:21]
	v_mfma_f32_16x16x32_bf16 v[2:5], v[144:147], v[218:221], v[2:5]
	v_mfma_f32_16x16x32_bf16 v[6:9], v[180:183], v[218:221], v[6:9]
	s_barrier
	s_setprio 0
	s_add_i32 s93, s93, 2
	s_add_u32 vcc_lo, vcc_lo, 0x100
	s_addc_u32 vcc_hi, vcc_hi, 0
	s_add_u32 s84, s84, 0x100
	s_addc_u32 s85, s85, 0
	s_cmp_gt_u32 s93, 13
	s_cbranch_scc0 .LBB0_111
	s_and_b64 vcc, exec, s[60:61]
	s_cbranch_vccz .LBB0_114
	s_barrier

.LBB0_208:
	s_add_u32 s72, s90, 0xfffe0080
	s_addc_u32 s73, s91, -1
	s_add_i32 s79, 0, 0x10000
	s_cmp_eq_u32 s78, 4
	s_cselect_b32 s95, s89, s73
	s_cselect_b32 s94, s88, s72
	s_cselect_b32 s93, s61, s77
	s_cselect_b32 s92, s60, s76
	s_add_i32 s72, 0, 0x14000
	v_add_u32_e32 v14, s79, v189
	v_add_u32_e32 v26, s72, v189
	ds_read_b128 v[2:5], v14
	ds_read_b128 v[6:9], v14 offset:1024
	ds_read_b128 v[10:13], v14 offset:2048
	ds_read_b128 v[14:17], v14 offset:3072
	ds_read_b128 v[18:21], v26
	ds_read_b128 v[22:25], v26 offset:1024
	ds_read_b128 v[192:195], v26 offset:2048
	ds_read_b128 v[196:199], v26 offset:3072
	v_lshl_add_u64 v[216:217], s[90:91], 0, v[166:167]
	s_add_i32 m0, s11, 0xc000
	ds_read_b128 v[178:181], v190
	ds_read_b128 v[182:185], v190 offset:1024
	ds_read_b128 v[200:203], v190 offset:2048
	ds_read_b128 v[204:207], v190 offset:3072
	ds_read_b128 v[208:211], v190 offset:4096
	ds_read_b128 v[212:215], v190 offset:5120
	ds_read_b128 v[226:229], v190 offset:6144
	ds_read_b128 v[230:233], v190 offset:7168
	global_load_lds_dwordx4 v[216:217], off
	v_lshl_add_u64 v[216:217], s[90:91], 0, v[176:177]
	s_add_i32 m0, s11, 0xe000
	s_nop 0
	global_load_lds_dwordx4 v[216:217], off
	s_waitcnt vmcnt(8)
	s_waitcnt lgkmcnt(0)
	s_setprio 1
	s_barrier
	v_mfma_scale_f32_16x16x128_f8f6f4 v[148:151], v[2:9], v[178:185], v[148:151], v186, v186 op_sel_hi:[0,0,0]
	v_mfma_scale_f32_16x16x128_f8f6f4 v[152:155], v[10:17], v[178:185], v[152:155], v186, v186 op_sel_hi:[0,0,0]
	v_mfma_scale_f32_16x16x128_f8f6f4 v[124:127], v[2:9], v[200:207], v[124:127], v186, v186 op_sel_hi:[0,0,0]
	v_mfma_scale_f32_16x16x128_f8f6f4 v[128:131], v[10:17], v[200:207], v[128:131], v186, v186 op_sel_hi:[0,0,0]
	v_mfma_scale_f32_16x16x128_f8f6f4 v[108:111], v[2:9], v[208:215], v[108:111], v186, v186 op_sel_hi:[0,0,0]
	v_mfma_scale_f32_16x16x128_f8f6f4 v[112:115], v[10:17], v[208:215], v[112:115], v186, v186 op_sel_hi:[0,0,0]
	v_mfma_scale_f32_16x16x128_f8f6f4 v[92:95], v[2:9], v[226:233], v[92:95], v186, v186 op_sel_hi:[0,0,0]
	v_mfma_scale_f32_16x16x128_f8f6f4 v[96:99], v[10:17], v[226:233], v[96:99], v186, v186 op_sel_hi:[0,0,0]
	s_setprio 0
	s_setprio 1
	v_mfma_scale_f32_16x16x128_f8f6f4 v[140:143], v[18:25], v[178:185], v[140:143], v186, v186 op_sel_hi:[0,0,0]
	v_mfma_scale_f32_16x16x128_f8f6f4 v[144:147], v[192:199], v[178:185], v[144:147], v186, v186 op_sel_hi:[0,0,0]
	v_mfma_scale_f32_16x16x128_f8f6f4 v[132:135], v[18:25], v[200:207], v[132:135], v186, v186 op_sel_hi:[0,0,0]
	v_mfma_scale_f32_16x16x128_f8f6f4 v[136:139], v[192:199], v[200:207], v[136:139], v186, v186 op_sel_hi:[0,0,0]
	v_mfma_scale_f32_16x16x128_f8f6f4 v[116:119], v[18:25], v[208:215], v[116:119], v186, v186 op_sel_hi:[0,0,0]
	v_mfma_scale_f32_16x16x128_f8f6f4 v[120:123], v[192:199], v[208:215], v[120:123], v186, v186 op_sel_hi:[0,0,0]
	v_mfma_scale_f32_16x16x128_f8f6f4 v[100:103], v[18:25], v[226:233], v[100:103], v186, v186 op_sel_hi:[0,0,0]
	v_mfma_scale_f32_16x16x128_f8f6f4 v[104:107], v[192:199], v[226:233], v[104:107], v186, v186 op_sel_hi:[0,0,0]
	s_barrier
	s_setprio 0
	s_add_i32 s73, s79, s8
	v_lshl_add_u64 v[178:179], s[92:93], 0, v[158:159]
	s_mov_b32 m0, s73
	ds_read_b128 v[200:203], v190 offset:16384
	ds_read_b128 v[204:207], v190 offset:17408
	ds_read_b128 v[208:211], v190 offset:18432
	ds_read_b128 v[212:215], v190 offset:19456
	ds_read_b128 v[226:229], v190 offset:20480
	ds_read_b128 v[230:233], v190 offset:21504
	ds_read_b128 v[234:237], v190 offset:22528
	ds_read_b128 v[238:241], v190 offset:23552
	global_load_lds_dwordx4 v[178:179], off
	s_add_i32 m0, s73, 0x2000
	s_add_u32 s80, s92, 0x20000
	v_lshl_add_u64 v[180:181], s[92:93], 0, v[162:163]
	s_addc_u32 s81, s93, 0
	s_add_i32 s72, s72, s8
	global_load_lds_dwordx4 v[180:181], off
	v_lshl_add_u64 v[182:183], s[80:81], 0, v[158:159]
	s_mov_b32 m0, s72
	v_lshl_add_u64 v[184:185], s[94:95], 0, v[160:161]
	global_load_lds_dwordx4 v[182:183], off
	v_lshl_add_u64 v[182:183], s[80:81], 0, v[162:163]
	s_add_i32 m0, s72, 0x2000
	s_nop 0
	global_load_lds_dwordx4 v[182:183], off
	v_lshl_add_u64 v[182:183], s[94:95], 0, v[156:157]
	s_mov_b32 m0, s11
	s_nop 0
	global_load_lds_dwordx4 v[182:183], off
	s_mov_b32 m0, s16
	s_nop 0
	global_load_lds_dwordx4 v[184:185], off
	s_waitcnt vmcnt(8)
	s_waitcnt lgkmcnt(0)
	s_setprio 1
	s_barrier
	v_mfma_scale_f32_16x16x128_f8f6f4 v[76:79], v[2:9], v[200:207], v[76:79], v186, v186 op_sel_hi:[0,0,0]
	v_mfma_scale_f32_16x16x128_f8f6f4 v[80:83], v[10:17], v[200:207], v[80:83], v186, v186 op_sel_hi:[0,0,0]
	v_mfma_scale_f32_16x16x128_f8f6f4 v[60:63], v[2:9], v[208:215], v[60:63], v186, v186 op_sel_hi:[0,0,0]
	v_mfma_scale_f32_16x16x128_f8f6f4 v[64:67], v[10:17], v[208:215], v[64:67], v186, v186 op_sel_hi:[0,0,0]
	v_mfma_scale_f32_16x16x128_f8f6f4 v[44:47], v[2:9], v[226:233], v[44:47], v186, v186 op_sel_hi:[0,0,0]
	v_mfma_scale_f32_16x16x128_f8f6f4 v[48:51], v[10:17], v[226:233], v[48:51], v186, v186 op_sel_hi:[0,0,0]
	v_mfma_scale_f32_16x16x128_f8f6f4 v[28:31], v[2:9], v[234:241], v[28:31], v186, v186 op_sel_hi:[0,0,0]
	v_mfma_scale_f32_16x16x128_f8f6f4 v[32:35], v[10:17], v[234:241], v[32:35], v186, v186 op_sel_hi:[0,0,0]
	s_setprio 0
	s_setprio 1
	v_mfma_scale_f32_16x16x128_f8f6f4 v[84:87], v[18:25], v[200:207], v[84:87], v186, v186 op_sel_hi:[0,0,0]
	v_mfma_scale_f32_16x16x128_f8f6f4 v[88:91], v[192:199], v[200:207], v[88:91], v186, v186 op_sel_hi:[0,0,0]
	v_mfma_scale_f32_16x16x128_f8f6f4 v[68:71], v[18:25], v[208:215], v[68:71], v186, v186 op_sel_hi:[0,0,0]
	v_mfma_scale_f32_16x16x128_f8f6f4 v[72:75], v[192:199], v[208:215], v[72:75], v186, v186 op_sel_hi:[0,0,0]
	v_mfma_scale_f32_16x16x128_f8f6f4 v[52:55], v[18:25], v[226:233], v[52:55], v186, v186 op_sel_hi:[0,0,0]
	v_mfma_scale_f32_16x16x128_f8f6f4 v[56:59], v[192:199], v[226:233], v[56:59], v186, v186 op_sel_hi:[0,0,0]
	v_mfma_scale_f32_16x16x128_f8f6f4 v[36:39], v[18:25], v[234:241], v[36:39], v186, v186 op_sel_hi:[0,0,0]
	v_mfma_scale_f32_16x16x128_f8f6f4 v[40:43], v[192:199], v[234:241], v[40:43], v186, v186 op_sel_hi:[0,0,0]
	s_barrier
	s_setprio 0
	s_add_i32 s79, 0, 0x18000
	s_add_i32 s72, 0, 0x1c000
	v_add_u32_e32 v2, s79, v189
	v_add_u32_e32 v22, s72, v189
	ds_read_b128 v[10:13], v2
	ds_read_b128 v[14:17], v2 offset:1024
	ds_read_b128 v[192:195], v2 offset:2048
	ds_read_b128 v[196:199], v2 offset:3072
	ds_read_b128 v[2:5], v22
	ds_read_b128 v[6:9], v22 offset:1024
	ds_read_b128 v[18:21], v22 offset:2048
	ds_read_b128 v[22:25], v22 offset:3072
	s_add_u32 s80, s94, 0x20000
	s_addc_u32 s81, s95, 0
	s_mov_b32 m0, s17
	v_lshl_add_u64 v[216:217], s[80:81], 0, v[156:157]
	ds_read_b128 v[200:203], v190 offset:32768
	ds_read_b128 v[204:207], v190 offset:33792
	ds_read_b128 v[208:211], v190 offset:34816
	ds_read_b128 v[212:215], v190 offset:35840
	ds_read_b128 v[226:229], v190 offset:36864
	ds_read_b128 v[230:233], v190 offset:37888
	ds_read_b128 v[234:237], v190 offset:38912
	ds_read_b128 v[238:241], v190 offset:39936
	global_load_lds_dwordx4 v[216:217], off
	v_lshl_add_u64 v[216:217], s[80:81], 0, v[160:161]
	s_mov_b32 m0, s22
	s_nop 0
	global_load_lds_dwordx4 v[216:217], off
	s_waitcnt vmcnt(8)
	s_waitcnt lgkmcnt(0)
	s_setprio 1
	s_barrier
	v_mfma_scale_f32_16x16x128_f8f6f4 v[148:151], v[10:17], v[200:207], v[148:151], v186, v186 op_sel_hi:[0,0,0]
	v_mfma_scale_f32_16x16x128_f8f6f4 v[152:155], v[192:199], v[200:207], v[152:155], v186, v186 op_sel_hi:[0,0,0]
	v_mfma_scale_f32_16x16x128_f8f6f4 v[124:127], v[10:17], v[208:215], v[124:127], v186, v186 op_sel_hi:[0,0,0]
	v_mfma_scale_f32_16x16x128_f8f6f4 v[128:131], v[192:199], v[208:215], v[128:131], v186, v186 op_sel_hi:[0,0,0]
	v_mfma_scale_f32_16x16x128_f8f6f4 v[108:111], v[10:17], v[226:233], v[108:111], v186, v186 op_sel_hi:[0,0,0]
	v_mfma_scale_f32_16x16x128_f8f6f4 v[112:115], v[192:199], v[226:233], v[112:115], v186, v186 op_sel_hi:[0,0,0]
	v_mfma_scale_f32_16x16x128_f8f6f4 v[92:95], v[10:17], v[234:241], v[92:95], v186, v186 op_sel_hi:[0,0,0]
	v_mfma_scale_f32_16x16x128_f8f6f4 v[96:99], v[192:199], v[234:241], v[96:99], v186, v186 op_sel_hi:[0,0,0]
	s_setprio 0
	s_setprio 1
	v_mfma_scale_f32_16x16x128_f8f6f4 v[140:143], v[2:9], v[200:207], v[140:143], v186, v186 op_sel_hi:[0,0,0]
	v_mfma_scale_f32_16x16x128_f8f6f4 v[144:147], v[18:25], v[200:207], v[144:147], v186, v186 op_sel_hi:[0,0,0]
	v_mfma_scale_f32_16x16x128_f8f6f4 v[132:135], v[2:9], v[208:215], v[132:135], v186, v186 op_sel_hi:[0,0,0]
	v_mfma_scale_f32_16x16x128_f8f6f4 v[136:139], v[18:25], v[208:215], v[136:139], v186, v186 op_sel_hi:[0,0,0]
	v_mfma_scale_f32_16x16x128_f8f6f4 v[116:119], v[2:9], v[226:233], v[116:119], v186, v186 op_sel_hi:[0,0,0]
	v_mfma_scale_f32_16x16x128_f8f6f4 v[120:123], v[18:25], v[226:233], v[120:123], v186, v186 op_sel_hi:[0,0,0]
	v_mfma_scale_f32_16x16x128_f8f6f4 v[100:103], v[2:9], v[234:241], v[100:103], v186, v186 op_sel_hi:[0,0,0]
	v_mfma_scale_f32_16x16x128_f8f6f4 v[104:107], v[18:25], v[234:241], v[104:107], v186, v186 op_sel_hi:[0,0,0]
	s_barrier
	s_setprio 0
	s_add_i32 s73, s79, s8
	v_lshl_add_u64 v[178:179], v[178:179], 0, s[82:83]
	s_mov_b32 m0, s73
	ds_read_b128 v[200:203], v190 offset:49152
	ds_read_b128 v[204:207], v190 offset:50176
	ds_read_b128 v[208:211], v190 offset:51200
	ds_read_b128 v[212:215], v190 offset:52224
	ds_read_b128 v[226:229], v190 offset:53248
	ds_read_b128 v[230:233], v190 offset:54272
	ds_read_b128 v[234:237], v190 offset:55296
	ds_read_b128 v[238:241], v190 offset:56320
	global_load_lds_dwordx4 v[178:179], off
	s_add_i32 m0, s73, 0x2000
	s_add_u32 s80, s92, 0x20080
	v_lshl_add_u64 v[178:179], v[180:181], 0, s[82:83]
	s_addc_u32 s81, s93, 0
	s_add_i32 s72, s72, s8
	global_load_lds_dwordx4 v[178:179], off
	v_lshl_add_u64 v[178:179], s[80:81], 0, v[158:159]
	s_mov_b32 m0, s72
	s_nop 0
	global_load_lds_dwordx4 v[178:179], off
	v_lshl_add_u64 v[178:179], s[80:81], 0, v[162:163]
	s_add_i32 m0, s72, 0x2000
	s_nop 0
	global_load_lds_dwordx4 v[178:179], off
	v_lshl_add_u64 v[178:179], v[182:183], 0, s[82:83]
	s_mov_b32 m0, s26
	s_nop 0
	global_load_lds_dwordx4 v[178:179], off
	v_lshl_add_u64 v[178:179], v[184:185], 0, s[82:83]
	s_mov_b32 m0, s27
	s_nop 0
	global_load_lds_dwordx4 v[178:179], off
	s_waitcnt vmcnt(8)
	s_waitcnt lgkmcnt(0)
	s_setprio 1
	s_barrier
	v_mfma_scale_f32_16x16x128_f8f6f4 v[76:79], v[10:17], v[200:207], v[76:79], v186, v186 op_sel_hi:[0,0,0]
	v_mfma_scale_f32_16x16x128_f8f6f4 v[80:83], v[192:199], v[200:207], v[80:83], v186, v186 op_sel_hi:[0,0,0]
	v_mfma_scale_f32_16x16x128_f8f6f4 v[60:63], v[10:17], v[208:215], v[60:63], v186, v186 op_sel_hi:[0,0,0]
	v_mfma_scale_f32_16x16x128_f8f6f4 v[64:67], v[192:199], v[208:215], v[64:67], v186, v186 op_sel_hi:[0,0,0]
	v_mfma_scale_f32_16x16x128_f8f6f4 v[44:47], v[10:17], v[226:233], v[44:47], v186, v186 op_sel_hi:[0,0,0]
	v_mfma_scale_f32_16x16x128_f8f6f4 v[48:51], v[192:199], v[226:233], v[48:51], v186, v186 op_sel_hi:[0,0,0]
	v_mfma_scale_f32_16x16x128_f8f6f4 v[28:31], v[10:17], v[234:241], v[28:31], v186, v186 op_sel_hi:[0,0,0]
	v_mfma_scale_f32_16x16x128_f8f6f4 v[32:35], v[192:199], v[234:241], v[32:35], v186, v186 op_sel_hi:[0,0,0]
	s_setprio 0
	s_setprio 1
	v_mfma_scale_f32_16x16x128_f8f6f4 v[84:87], v[2:9], v[200:207], v[84:87], v186, v186 op_sel_hi:[0,0,0]
	v_mfma_scale_f32_16x16x128_f8f6f4 v[88:91], v[18:25], v[200:207], v[88:91], v186, v186 op_sel_hi:[0,0,0]
	v_mfma_scale_f32_16x16x128_f8f6f4 v[68:71], v[2:9], v[208:215], v[68:71], v186, v186 op_sel_hi:[0,0,0]
	v_mfma_scale_f32_16x16x128_f8f6f4 v[72:75], v[18:25], v[208:215], v[72:75], v186, v186 op_sel_hi:[0,0,0]
	v_mfma_scale_f32_16x16x128_f8f6f4 v[52:55], v[2:9], v[226:233], v[52:55], v186, v186 op_sel_hi:[0,0,0]
	v_mfma_scale_f32_16x16x128_f8f6f4 v[56:59], v[18:25], v[226:233], v[56:59], v186, v186 op_sel_hi:[0,0,0]
	v_mfma_scale_f32_16x16x128_f8f6f4 v[36:39], v[2:9], v[234:241], v[36:39], v186, v186 op_sel_hi:[0,0,0]
	v_mfma_scale_f32_16x16x128_f8f6f4 v[40:43], v[18:25], v[234:241], v[40:43], v186, v186 op_sel_hi:[0,0,0]
	s_barrier
	s_setprio 0
	s_add_i32 s78, s78, 2
	s_add_u32 s90, s90, 0x100
	s_addc_u32 s91, s91, 0
	s_add_u32 s76, s76, 0x100
	s_addc_u32 s77, s77, 0
	s_cmp_gt_u32 s78, 5
	s_cbranch_scc0 .LBB0_208
	s_and_b64 vcc, exec, s[30:31]
	s_cbranch_vccz .LBB0_211
	s_barrier

.LBB0_383:
	s_add_u32 s12, s52, 0xfffe0080
	s_addc_u32 s54, s53, -1
	s_add_i32 s72, 0, 0x10000
	s_cmp_eq_u32 s68, 4
	s_cselect_b32 s59, s37, s54
	s_cselect_b32 s58, s36, s12
	s_cselect_b32 s55, s21, s47
	s_cselect_b32 s54, s20, s35
	s_add_i32 s12, 0, 0x14000
	v_add_u32_e32 v14, s72, v190
	v_add_u32_e32 v26, s12, v190
	ds_read_b128 v[2:5], v14
	ds_read_b128 v[6:9], v14 offset:1024
	ds_read_b128 v[10:13], v14 offset:2048
	ds_read_b128 v[14:17], v14 offset:3072
	ds_read_b128 v[18:21], v26
	ds_read_b128 v[22:25], v26 offset:1024
	ds_read_b128 v[192:195], v26 offset:2048
	ds_read_b128 v[196:199], v26 offset:3072
	v_lshl_add_u64 v[216:217], s[52:53], 0, v[166:167]
	s_add_i32 m0, s11, 0xc000
	ds_read_b128 v[178:181], v191
	ds_read_b128 v[182:185], v191 offset:1024
	ds_read_b128 v[200:203], v191 offset:2048
	ds_read_b128 v[204:207], v191 offset:3072
	ds_read_b128 v[208:211], v191 offset:4096
	ds_read_b128 v[212:215], v191 offset:5120
	ds_read_b128 v[226:229], v191 offset:6144
	ds_read_b128 v[230:233], v191 offset:7168
	global_load_lds_dwordx4 v[216:217], off
	v_lshl_add_u64 v[216:217], s[52:53], 0, v[176:177]
	s_add_i32 m0, s11, 0xe000
	s_nop 0
	global_load_lds_dwordx4 v[216:217], off
	s_waitcnt vmcnt(8)
	s_waitcnt lgkmcnt(0)
	s_setprio 1
	s_barrier
	v_mfma_scale_f32_16x16x128_f8f6f4 v[140:143], v[2:9], v[178:185], v[140:143], v187, v187 op_sel_hi:[0,0,0]
	v_mfma_scale_f32_16x16x128_f8f6f4 v[144:147], v[10:17], v[178:185], v[144:147], v187, v187 op_sel_hi:[0,0,0]
	v_mfma_scale_f32_16x16x128_f8f6f4 v[124:127], v[2:9], v[200:207], v[124:127], v187, v187 op_sel_hi:[0,0,0]
	v_mfma_scale_f32_16x16x128_f8f6f4 v[128:131], v[10:17], v[200:207], v[128:131], v187, v187 op_sel_hi:[0,0,0]
	v_mfma_scale_f32_16x16x128_f8f6f4 v[108:111], v[2:9], v[208:215], v[108:111], v187, v187 op_sel_hi:[0,0,0]
	v_mfma_scale_f32_16x16x128_f8f6f4 v[112:115], v[10:17], v[208:215], v[112:115], v187, v187 op_sel_hi:[0,0,0]
	v_mfma_scale_f32_16x16x128_f8f6f4 v[76:79], v[2:9], v[226:233], v[76:79], v187, v187 op_sel_hi:[0,0,0]
	v_mfma_scale_f32_16x16x128_f8f6f4 v[84:87], v[10:17], v[226:233], v[84:87], v187, v187 op_sel_hi:[0,0,0]
	s_setprio 0
	s_setprio 1
	v_mfma_scale_f32_16x16x128_f8f6f4 v[148:151], v[18:25], v[178:185], v[148:151], v187, v187 op_sel_hi:[0,0,0]
	v_mfma_scale_f32_16x16x128_f8f6f4 v[152:155], v[192:199], v[178:185], v[152:155], v187, v187 op_sel_hi:[0,0,0]
	v_mfma_scale_f32_16x16x128_f8f6f4 v[132:135], v[18:25], v[200:207], v[132:135], v187, v187 op_sel_hi:[0,0,0]
	v_mfma_scale_f32_16x16x128_f8f6f4 v[136:139], v[192:199], v[200:207], v[136:139], v187, v187 op_sel_hi:[0,0,0]
	v_mfma_scale_f32_16x16x128_f8f6f4 v[116:119], v[18:25], v[208:215], v[116:119], v187, v187 op_sel_hi:[0,0,0]
	v_mfma_scale_f32_16x16x128_f8f6f4 v[120:123], v[192:199], v[208:215], v[120:123], v187, v187 op_sel_hi:[0,0,0]
	v_mfma_scale_f32_16x16x128_f8f6f4 v[96:99], v[18:25], v[226:233], v[96:99], v187, v187 op_sel_hi:[0,0,0]
	v_mfma_scale_f32_16x16x128_f8f6f4 v[104:107], v[192:199], v[226:233], v[104:107], v187, v187 op_sel_hi:[0,0,0]
	s_barrier
	s_setprio 0
	s_add_i32 s72, s72, s8
	v_lshl_add_u64 v[178:179], s[54:55], 0, v[158:159]
	s_mov_b32 m0, s72
	ds_read_b128 v[200:203], v191 offset:16384
	ds_read_b128 v[204:207], v191 offset:17408
	ds_read_b128 v[208:211], v191 offset:18432
	ds_read_b128 v[212:215], v191 offset:19456
	ds_read_b128 v[226:229], v191 offset:20480
	ds_read_b128 v[230:233], v191 offset:21504
	ds_read_b128 v[234:237], v191 offset:22528
	ds_read_b128 v[238:241], v191 offset:23552
	global_load_lds_dwordx4 v[178:179], off
	s_add_i32 m0, s72, 0x2000
	s_add_u32 s72, s54, 0x20000
	v_lshl_add_u64 v[180:181], s[54:55], 0, v[162:163]
	s_addc_u32 s73, s55, 0
	s_add_i32 s12, s12, s8
	global_load_lds_dwordx4 v[180:181], off
	v_lshl_add_u64 v[182:183], s[72:73], 0, v[158:159]
	s_mov_b32 m0, s12
	v_lshl_add_u64 v[184:185], s[58:59], 0, v[160:161]
	global_load_lds_dwordx4 v[182:183], off
	v_lshl_add_u64 v[182:183], s[72:73], 0, v[162:163]
	s_add_i32 m0, s12, 0x2000
	s_nop 0
	global_load_lds_dwordx4 v[182:183], off
	v_lshl_add_u64 v[182:183], s[58:59], 0, v[156:157]
	s_mov_b32 m0, s11
	s_nop 0
	global_load_lds_dwordx4 v[182:183], off
	s_mov_b32 m0, s16
	s_nop 0
	global_load_lds_dwordx4 v[184:185], off
	s_waitcnt vmcnt(8)
	s_waitcnt lgkmcnt(0)
	s_setprio 1
	s_barrier
	v_mfma_scale_f32_16x16x128_f8f6f4 v[80:83], v[2:9], v[200:207], v[80:83], v187, v187 op_sel_hi:[0,0,0]
	v_mfma_scale_f32_16x16x128_f8f6f4 v[88:91], v[10:17], v[200:207], v[88:91], v187, v187 op_sel_hi:[0,0,0]
	v_mfma_scale_f32_16x16x128_f8f6f4 v[60:63], v[2:9], v[208:215], v[60:63], v187, v187 op_sel_hi:[0,0,0]
	v_mfma_scale_f32_16x16x128_f8f6f4 v[64:67], v[10:17], v[208:215], v[64:67], v187, v187 op_sel_hi:[0,0,0]
	v_mfma_scale_f32_16x16x128_f8f6f4 v[44:47], v[2:9], v[226:233], v[44:47], v187, v187 op_sel_hi:[0,0,0]
	v_mfma_scale_f32_16x16x128_f8f6f4 v[48:51], v[10:17], v[226:233], v[48:51], v187, v187 op_sel_hi:[0,0,0]
	v_mfma_scale_f32_16x16x128_f8f6f4 v[28:31], v[2:9], v[234:241], v[28:31], v187, v187 op_sel_hi:[0,0,0]
	v_mfma_scale_f32_16x16x128_f8f6f4 v[32:35], v[10:17], v[234:241], v[32:35], v187, v187 op_sel_hi:[0,0,0]
	s_setprio 0
	s_setprio 1
	v_mfma_scale_f32_16x16x128_f8f6f4 v[92:95], v[18:25], v[200:207], v[92:95], v187, v187 op_sel_hi:[0,0,0]
	v_mfma_scale_f32_16x16x128_f8f6f4 v[100:103], v[192:199], v[200:207], v[100:103], v187, v187 op_sel_hi:[0,0,0]
	v_mfma_scale_f32_16x16x128_f8f6f4 v[68:71], v[18:25], v[208:215], v[68:71], v187, v187 op_sel_hi:[0,0,0]
	v_mfma_scale_f32_16x16x128_f8f6f4 v[72:75], v[192:199], v[208:215], v[72:75], v187, v187 op_sel_hi:[0,0,0]
	v_mfma_scale_f32_16x16x128_f8f6f4 v[52:55], v[18:25], v[226:233], v[52:55], v187, v187 op_sel_hi:[0,0,0]
	v_mfma_scale_f32_16x16x128_f8f6f4 v[56:59], v[192:199], v[226:233], v[56:59], v187, v187 op_sel_hi:[0,0,0]
	v_mfma_scale_f32_16x16x128_f8f6f4 v[36:39], v[18:25], v[234:241], v[36:39], v187, v187 op_sel_hi:[0,0,0]
	v_mfma_scale_f32_16x16x128_f8f6f4 v[40:43], v[192:199], v[234:241], v[40:43], v187, v187 op_sel_hi:[0,0,0]
	s_barrier
	s_setprio 0
	s_add_i32 s74, 0, 0x18000
	s_add_i32 s12, 0, 0x1c000
	v_add_u32_e32 v2, s74, v190
	v_add_u32_e32 v22, s12, v190
	ds_read_b128 v[10:13], v2
	ds_read_b128 v[14:17], v2 offset:1024
	ds_read_b128 v[192:195], v2 offset:2048
	ds_read_b128 v[196:199], v2 offset:3072
	ds_read_b128 v[2:5], v22
	ds_read_b128 v[6:9], v22 offset:1024
	ds_read_b128 v[18:21], v22 offset:2048
	ds_read_b128 v[22:25], v22 offset:3072
	s_add_u32 s58, s58, 0x20000
	s_addc_u32 s59, s59, 0
	s_mov_b32 m0, s17
	v_lshl_add_u64 v[216:217], s[58:59], 0, v[156:157]
	ds_read_b128 v[200:203], v191 offset:32768
	ds_read_b128 v[204:207], v191 offset:33792
	ds_read_b128 v[208:211], v191 offset:34816
	ds_read_b128 v[212:215], v191 offset:35840
	ds_read_b128 v[226:229], v191 offset:36864
	ds_read_b128 v[230:233], v191 offset:37888
	ds_read_b128 v[234:237], v191 offset:38912
	ds_read_b128 v[238:241], v191 offset:39936
	global_load_lds_dwordx4 v[216:217], off
	v_lshl_add_u64 v[216:217], s[58:59], 0, v[160:161]
	s_mov_b32 m0, s22
	s_nop 0
	global_load_lds_dwordx4 v[216:217], off
	s_waitcnt vmcnt(8)
	s_waitcnt lgkmcnt(0)
	s_setprio 1
	s_barrier
	v_mfma_scale_f32_16x16x128_f8f6f4 v[140:143], v[10:17], v[200:207], v[140:143], v187, v187 op_sel_hi:[0,0,0]
	v_mfma_scale_f32_16x16x128_f8f6f4 v[144:147], v[192:199], v[200:207], v[144:147], v187, v187 op_sel_hi:[0,0,0]
	v_mfma_scale_f32_16x16x128_f8f6f4 v[124:127], v[10:17], v[208:215], v[124:127], v187, v187 op_sel_hi:[0,0,0]
	v_mfma_scale_f32_16x16x128_f8f6f4 v[128:131], v[192:199], v[208:215], v[128:131], v187, v187 op_sel_hi:[0,0,0]
	v_mfma_scale_f32_16x16x128_f8f6f4 v[108:111], v[10:17], v[226:233], v[108:111], v187, v187 op_sel_hi:[0,0,0]
	v_mfma_scale_f32_16x16x128_f8f6f4 v[112:115], v[192:199], v[226:233], v[112:115], v187, v187 op_sel_hi:[0,0,0]
	v_mfma_scale_f32_16x16x128_f8f6f4 v[76:79], v[10:17], v[234:241], v[76:79], v187, v187 op_sel_hi:[0,0,0]
	v_mfma_scale_f32_16x16x128_f8f6f4 v[84:87], v[192:199], v[234:241], v[84:87], v187, v187 op_sel_hi:[0,0,0]
	s_setprio 0
	s_setprio 1
	v_mfma_scale_f32_16x16x128_f8f6f4 v[148:151], v[2:9], v[200:207], v[148:151], v187, v187 op_sel_hi:[0,0,0]
	v_mfma_scale_f32_16x16x128_f8f6f4 v[152:155], v[18:25], v[200:207], v[152:155], v187, v187 op_sel_hi:[0,0,0]
	v_mfma_scale_f32_16x16x128_f8f6f4 v[132:135], v[2:9], v[208:215], v[132:135], v187, v187 op_sel_hi:[0,0,0]
	v_mfma_scale_f32_16x16x128_f8f6f4 v[136:139], v[18:25], v[208:215], v[136:139], v187, v187 op_sel_hi:[0,0,0]
	v_mfma_scale_f32_16x16x128_f8f6f4 v[116:119], v[2:9], v[226:233], v[116:119], v187, v187 op_sel_hi:[0,0,0]
	v_mfma_scale_f32_16x16x128_f8f6f4 v[120:123], v[18:25], v[226:233], v[120:123], v187, v187 op_sel_hi:[0,0,0]
	v_mfma_scale_f32_16x16x128_f8f6f4 v[96:99], v[2:9], v[234:241], v[96:99], v187, v187 op_sel_hi:[0,0,0]
	v_mfma_scale_f32_16x16x128_f8f6f4 v[104:107], v[18:25], v[234:241], v[104:107], v187, v187 op_sel_hi:[0,0,0]
	s_barrier
	s_setprio 0
	s_add_i32 s58, s74, s8
	v_lshl_add_u64 v[178:179], v[178:179], 0, s[82:83]
	s_mov_b32 m0, s58
	ds_read_b128 v[200:203], v191 offset:49152
	ds_read_b128 v[204:207], v191 offset:50176
	ds_read_b128 v[208:211], v191 offset:51200
	ds_read_b128 v[212:215], v191 offset:52224
	ds_read_b128 v[226:229], v191 offset:53248
	ds_read_b128 v[230:233], v191 offset:54272
	ds_read_b128 v[234:237], v191 offset:55296
	ds_read_b128 v[238:241], v191 offset:56320
	global_load_lds_dwordx4 v[178:179], off
	s_add_i32 m0, s58, 0x2000
	s_add_u32 s54, s54, 0x20080
	v_lshl_add_u64 v[178:179], v[180:181], 0, s[82:83]
	s_addc_u32 s55, s55, 0
	s_add_i32 s12, s12, s8
	global_load_lds_dwordx4 v[178:179], off
	v_lshl_add_u64 v[178:179], s[54:55], 0, v[158:159]
	s_mov_b32 m0, s12
	s_nop 0
	global_load_lds_dwordx4 v[178:179], off
	v_lshl_add_u64 v[178:179], s[54:55], 0, v[162:163]
	s_add_i32 m0, s12, 0x2000
	s_nop 0
	global_load_lds_dwordx4 v[178:179], off
	v_lshl_add_u64 v[178:179], v[182:183], 0, s[82:83]
	s_mov_b32 m0, s23
	s_nop 0
	global_load_lds_dwordx4 v[178:179], off
	v_lshl_add_u64 v[178:179], v[184:185], 0, s[82:83]
	s_mov_b32 m0, s26
	s_nop 0
	global_load_lds_dwordx4 v[178:179], off
	s_waitcnt vmcnt(8)
	s_waitcnt lgkmcnt(0)
	s_setprio 1
	s_barrier
	v_mfma_scale_f32_16x16x128_f8f6f4 v[80:83], v[10:17], v[200:207], v[80:83], v187, v187 op_sel_hi:[0,0,0]
	v_mfma_scale_f32_16x16x128_f8f6f4 v[88:91], v[192:199], v[200:207], v[88:91], v187, v187 op_sel_hi:[0,0,0]
	v_mfma_scale_f32_16x16x128_f8f6f4 v[60:63], v[10:17], v[208:215], v[60:63], v187, v187 op_sel_hi:[0,0,0]
	v_mfma_scale_f32_16x16x128_f8f6f4 v[64:67], v[192:199], v[208:215], v[64:67], v187, v187 op_sel_hi:[0,0,0]
	v_mfma_scale_f32_16x16x128_f8f6f4 v[44:47], v[10:17], v[226:233], v[44:47], v187, v187 op_sel_hi:[0,0,0]
	v_mfma_scale_f32_16x16x128_f8f6f4 v[48:51], v[192:199], v[226:233], v[48:51], v187, v187 op_sel_hi:[0,0,0]
	v_mfma_scale_f32_16x16x128_f8f6f4 v[28:31], v[10:17], v[234:241], v[28:31], v187, v187 op_sel_hi:[0,0,0]
	v_mfma_scale_f32_16x16x128_f8f6f4 v[32:35], v[192:199], v[234:241], v[32:35], v187, v187 op_sel_hi:[0,0,0]
	s_setprio 0
	s_setprio 1
	v_mfma_scale_f32_16x16x128_f8f6f4 v[92:95], v[2:9], v[200:207], v[92:95], v187, v187 op_sel_hi:[0,0,0]
	v_mfma_scale_f32_16x16x128_f8f6f4 v[100:103], v[18:25], v[200:207], v[100:103], v187, v187 op_sel_hi:[0,0,0]
	v_mfma_scale_f32_16x16x128_f8f6f4 v[68:71], v[2:9], v[208:215], v[68:71], v187, v187 op_sel_hi:[0,0,0]
	v_mfma_scale_f32_16x16x128_f8f6f4 v[72:75], v[18:25], v[208:215], v[72:75], v187, v187 op_sel_hi:[0,0,0]
	v_mfma_scale_f32_16x16x128_f8f6f4 v[52:55], v[2:9], v[226:233], v[52:55], v187, v187 op_sel_hi:[0,0,0]
	v_mfma_scale_f32_16x16x128_f8f6f4 v[56:59], v[18:25], v[226:233], v[56:59], v187, v187 op_sel_hi:[0,0,0]
	v_mfma_scale_f32_16x16x128_f8f6f4 v[36:39], v[2:9], v[234:241], v[36:39], v187, v187 op_sel_hi:[0,0,0]
	v_mfma_scale_f32_16x16x128_f8f6f4 v[40:43], v[18:25], v[234:241], v[40:43], v187, v187 op_sel_hi:[0,0,0]
	s_barrier
	s_setprio 0
	s_add_i32 s68, s68, 2
	s_add_u32 s52, s52, 0x100
	s_addc_u32 s53, s53, 0
	s_add_u32 s35, s35, 0x100
	s_addc_u32 s47, s47, 0
	s_cmp_gt_u32 s68, 5
	s_cbranch_scc0 .LBB0_383
	s_and_b64 vcc, exec, s[30:31]
	s_cbranch_vccz .LBB0_386
	s_barrier

.LBB0_492:
	s_add_i32 s12, s20, 0xf2de0080
	s_cmp_lg_u32 s36, 4
	s_cselect_b32 s12, s12, 0
	s_add_u32 s30, s84, s12
	s_addc_u32 s31, s85, 0
	s_add_i32 s37, 0, 0x10000
	s_add_u32 s28, s0, s12
	s_addc_u32 s29, s1, 0
	s_add_i32 s12, 0, 0x14000
	v_add_u32_e32 v14, s37, v186
	v_add_u32_e32 v166, s12, v186
	ds_read_b128 v[2:5], v14
	ds_read_b128 v[6:9], v14 offset:1024
	ds_read_b128 v[10:13], v14 offset:2048
	ds_read_b128 v[14:17], v14 offset:3072
	ds_read_b128 v[18:21], v166
	ds_read_b128 v[22:25], v166 offset:1024
	ds_read_b128 v[188:191], v166 offset:2048
	ds_read_b128 v[192:195], v166 offset:3072
	v_lshl_add_u64 v[166:167], v[162:163], 0, s[20:21]
	s_add_i32 m0, s17, 0xc000
	ds_read_b128 v[196:199], v187
	ds_read_b128 v[200:203], v187 offset:1024
	ds_read_b128 v[204:207], v187 offset:2048
	ds_read_b128 v[208:211], v187 offset:3072
	ds_read_b128 v[212:215], v187 offset:4096
	ds_read_b128 v[216:219], v187 offset:5120
	ds_read_b128 v[226:229], v187 offset:6144
	ds_read_b128 v[230:233], v187 offset:7168
	global_load_lds_dwordx4 v[166:167], off
	v_lshl_add_u64 v[166:167], v[164:165], 0, s[20:21]
	s_add_i32 m0, s17, 0xe000
	s_nop 0
	global_load_lds_dwordx4 v[166:167], off
	s_waitcnt vmcnt(8)
	s_waitcnt lgkmcnt(0)
	s_setprio 1
	s_barrier
	v_mfma_scale_f32_16x16x128_f8f6f4 v[144:147], v[2:9], v[196:203], v[144:147], v183, v183 op_sel_hi:[0,0,0]
	v_mfma_scale_f32_16x16x128_f8f6f4 v[148:151], v[10:17], v[196:203], v[148:151], v183, v183 op_sel_hi:[0,0,0]
	v_mfma_scale_f32_16x16x128_f8f6f4 v[124:127], v[2:9], v[204:211], v[124:127], v183, v183 op_sel_hi:[0,0,0]
	v_mfma_scale_f32_16x16x128_f8f6f4 v[128:131], v[10:17], v[204:211], v[128:131], v183, v183 op_sel_hi:[0,0,0]
	v_mfma_scale_f32_16x16x128_f8f6f4 v[108:111], v[2:9], v[212:219], v[108:111], v183, v183 op_sel_hi:[0,0,0]
	v_mfma_scale_f32_16x16x128_f8f6f4 v[112:115], v[10:17], v[212:219], v[112:115], v183, v183 op_sel_hi:[0,0,0]
	v_mfma_scale_f32_16x16x128_f8f6f4 v[92:95], v[2:9], v[226:233], v[92:95], v183, v183 op_sel_hi:[0,0,0]
	v_mfma_scale_f32_16x16x128_f8f6f4 v[96:99], v[10:17], v[226:233], v[96:99], v183, v183 op_sel_hi:[0,0,0]
	s_setprio 0
	s_setprio 1
	v_mfma_scale_f32_16x16x128_f8f6f4 v[152:155], v[18:25], v[196:203], v[152:155], v183, v183 op_sel_hi:[0,0,0]
	v_mfma_scale_f32_16x16x128_f8f6f4 v[140:143], v[188:195], v[196:203], v[140:143], v183, v183 op_sel_hi:[0,0,0]
	v_mfma_scale_f32_16x16x128_f8f6f4 v[132:135], v[18:25], v[204:211], v[132:135], v183, v183 op_sel_hi:[0,0,0]
	v_mfma_scale_f32_16x16x128_f8f6f4 v[136:139], v[188:195], v[204:211], v[136:139], v183, v183 op_sel_hi:[0,0,0]
	v_mfma_scale_f32_16x16x128_f8f6f4 v[116:119], v[18:25], v[212:219], v[116:119], v183, v183 op_sel_hi:[0,0,0]
	v_mfma_scale_f32_16x16x128_f8f6f4 v[120:123], v[188:195], v[212:219], v[120:123], v183, v183 op_sel_hi:[0,0,0]
	v_mfma_scale_f32_16x16x128_f8f6f4 v[100:103], v[18:25], v[226:233], v[100:103], v183, v183 op_sel_hi:[0,0,0]
	v_mfma_scale_f32_16x16x128_f8f6f4 v[104:107], v[188:195], v[226:233], v[104:107], v183, v183 op_sel_hi:[0,0,0]
	s_barrier
	s_setprio 0
	s_add_i32 s37, s37, s16
	v_lshl_add_u64 v[166:167], s[28:29], 0, v[26:27]
	s_mov_b32 m0, s37
	ds_read_b128 v[196:199], v187 offset:16384
	ds_read_b128 v[200:203], v187 offset:17408
	ds_read_b128 v[204:207], v187 offset:18432
	ds_read_b128 v[208:211], v187 offset:19456
	ds_read_b128 v[212:215], v187 offset:20480
	ds_read_b128 v[216:219], v187 offset:21504
	ds_read_b128 v[226:229], v187 offset:22528
	ds_read_b128 v[230:233], v187 offset:23552
	global_load_lds_dwordx4 v[166:167], off
	s_add_i32 m0, s37, 0x2000
	s_add_u32 s38, s28, 0x20000
	v_lshl_add_u64 v[176:177], s[28:29], 0, v[160:161]
	s_addc_u32 s39, s29, 0
	s_add_i32 s12, s12, s16
	global_load_lds_dwordx4 v[176:177], off
	v_lshl_add_u64 v[178:179], s[38:39], 0, v[26:27]
	s_mov_b32 m0, s12
	v_lshl_add_u64 v[180:181], s[30:31], 0, v[158:159]
	global_load_lds_dwordx4 v[178:179], off
	v_lshl_add_u64 v[178:179], s[38:39], 0, v[160:161]
	s_add_i32 m0, s12, 0x2000
	s_nop 0
	global_load_lds_dwordx4 v[178:179], off
	v_lshl_add_u64 v[178:179], s[30:31], 0, v[156:157]
	s_mov_b32 m0, s17
	s_nop 0
	global_load_lds_dwordx4 v[178:179], off
	s_mov_b32 m0, s22
	s_nop 0
	global_load_lds_dwordx4 v[180:181], off
	s_waitcnt vmcnt(8)
	s_waitcnt lgkmcnt(0)
	s_setprio 1
	s_barrier
	v_mfma_scale_f32_16x16x128_f8f6f4 v[76:79], v[2:9], v[196:203], v[76:79], v183, v183 op_sel_hi:[0,0,0]
	v_mfma_scale_f32_16x16x128_f8f6f4 v[80:83], v[10:17], v[196:203], v[80:83], v183, v183 op_sel_hi:[0,0,0]
	v_mfma_scale_f32_16x16x128_f8f6f4 v[60:63], v[2:9], v[204:211], v[60:63], v183, v183 op_sel_hi:[0,0,0]
	v_mfma_scale_f32_16x16x128_f8f6f4 v[64:67], v[10:17], v[204:211], v[64:67], v183, v183 op_sel_hi:[0,0,0]
	v_mfma_scale_f32_16x16x128_f8f6f4 v[44:47], v[2:9], v[212:219], v[44:47], v183, v183 op_sel_hi:[0,0,0]
	v_mfma_scale_f32_16x16x128_f8f6f4 v[48:51], v[10:17], v[212:219], v[48:51], v183, v183 op_sel_hi:[0,0,0]
	v_mfma_scale_f32_16x16x128_f8f6f4 v[28:31], v[2:9], v[226:233], v[28:31], v183, v183 op_sel_hi:[0,0,0]
	v_mfma_scale_f32_16x16x128_f8f6f4 v[32:35], v[10:17], v[226:233], v[32:35], v183, v183 op_sel_hi:[0,0,0]
	s_setprio 0
	s_setprio 1
	v_mfma_scale_f32_16x16x128_f8f6f4 v[84:87], v[18:25], v[196:203], v[84:87], v183, v183 op_sel_hi:[0,0,0]
	v_mfma_scale_f32_16x16x128_f8f6f4 v[88:91], v[188:195], v[196:203], v[88:91], v183, v183 op_sel_hi:[0,0,0]
	v_mfma_scale_f32_16x16x128_f8f6f4 v[68:71], v[18:25], v[204:211], v[68:71], v183, v183 op_sel_hi:[0,0,0]
	v_mfma_scale_f32_16x16x128_f8f6f4 v[72:75], v[188:195], v[204:211], v[72:75], v183, v183 op_sel_hi:[0,0,0]
	v_mfma_scale_f32_16x16x128_f8f6f4 v[52:55], v[18:25], v[212:219], v[52:55], v183, v183 op_sel_hi:[0,0,0]
	v_mfma_scale_f32_16x16x128_f8f6f4 v[56:59], v[188:195], v[212:219], v[56:59], v183, v183 op_sel_hi:[0,0,0]
	v_mfma_scale_f32_16x16x128_f8f6f4 v[40:43], v[18:25], v[226:233], v[40:43], v183, v183 op_sel_hi:[0,0,0]
	v_mfma_scale_f32_16x16x128_f8f6f4 v[36:39], v[188:195], v[226:233], v[36:39], v183, v183 op_sel_hi:[0,0,0]
	s_barrier
	s_setprio 0
	s_add_i32 s37, 0, 0x18000
	s_add_i32 s12, 0, 0x1c000
	v_add_u32_e32 v2, s37, v186
	v_add_u32_e32 v22, s12, v186
	ds_read_b128 v[10:13], v2
	ds_read_b128 v[14:17], v2 offset:1024
	ds_read_b128 v[188:191], v2 offset:2048
	ds_read_b128 v[192:195], v2 offset:3072
	ds_read_b128 v[2:5], v22
	ds_read_b128 v[6:9], v22 offset:1024
	ds_read_b128 v[18:21], v22 offset:2048
	ds_read_b128 v[22:25], v22 offset:3072
	s_add_u32 s30, s30, 0x20000
	s_addc_u32 s31, s31, 0
	s_mov_b32 m0, s23
	v_lshl_add_u64 v[220:221], s[30:31], 0, v[156:157]
	ds_read_b128 v[196:199], v187 offset:32768
	ds_read_b128 v[200:203], v187 offset:33792
	ds_read_b128 v[204:207], v187 offset:34816
	ds_read_b128 v[208:211], v187 offset:35840
	ds_read_b128 v[212:215], v187 offset:36864
	ds_read_b128 v[216:219], v187 offset:37888
	ds_read_b128 v[226:229], v187 offset:38912
	ds_read_b128 v[230:233], v187 offset:39936
	global_load_lds_dwordx4 v[220:221], off
	v_lshl_add_u64 v[220:221], s[30:31], 0, v[158:159]
	s_mov_b32 m0, s26
	s_nop 0
	global_load_lds_dwordx4 v[220:221], off
	s_waitcnt vmcnt(8)
	s_waitcnt lgkmcnt(0)
	s_setprio 1
	s_barrier
	v_mfma_scale_f32_16x16x128_f8f6f4 v[144:147], v[10:17], v[196:203], v[144:147], v183, v183 op_sel_hi:[0,0,0]
	v_mfma_scale_f32_16x16x128_f8f6f4 v[148:151], v[188:195], v[196:203], v[148:151], v183, v183 op_sel_hi:[0,0,0]
	v_mfma_scale_f32_16x16x128_f8f6f4 v[124:127], v[10:17], v[204:211], v[124:127], v183, v183 op_sel_hi:[0,0,0]
	v_mfma_scale_f32_16x16x128_f8f6f4 v[128:131], v[188:195], v[204:211], v[128:131], v183, v183 op_sel_hi:[0,0,0]
	v_mfma_scale_f32_16x16x128_f8f6f4 v[108:111], v[10:17], v[212:219], v[108:111], v183, v183 op_sel_hi:[0,0,0]
	v_mfma_scale_f32_16x16x128_f8f6f4 v[112:115], v[188:195], v[212:219], v[112:115], v183, v183 op_sel_hi:[0,0,0]
	v_mfma_scale_f32_16x16x128_f8f6f4 v[92:95], v[10:17], v[226:233], v[92:95], v183, v183 op_sel_hi:[0,0,0]
	v_mfma_scale_f32_16x16x128_f8f6f4 v[96:99], v[188:195], v[226:233], v[96:99], v183, v183 op_sel_hi:[0,0,0]
	s_setprio 0
	s_setprio 1
	v_mfma_scale_f32_16x16x128_f8f6f4 v[152:155], v[2:9], v[196:203], v[152:155], v183, v183 op_sel_hi:[0,0,0]
	v_mfma_scale_f32_16x16x128_f8f6f4 v[140:143], v[18:25], v[196:203], v[140:143], v183, v183 op_sel_hi:[0,0,0]
	v_mfma_scale_f32_16x16x128_f8f6f4 v[132:135], v[2:9], v[204:211], v[132:135], v183, v183 op_sel_hi:[0,0,0]
	v_mfma_scale_f32_16x16x128_f8f6f4 v[136:139], v[18:25], v[204:211], v[136:139], v183, v183 op_sel_hi:[0,0,0]
	v_mfma_scale_f32_16x16x128_f8f6f4 v[116:119], v[2:9], v[212:219], v[116:119], v183, v183 op_sel_hi:[0,0,0]
	v_mfma_scale_f32_16x16x128_f8f6f4 v[120:123], v[18:25], v[212:219], v[120:123], v183, v183 op_sel_hi:[0,0,0]
	v_mfma_scale_f32_16x16x128_f8f6f4 v[100:103], v[2:9], v[226:233], v[100:103], v183, v183 op_sel_hi:[0,0,0]
	v_mfma_scale_f32_16x16x128_f8f6f4 v[104:107], v[18:25], v[226:233], v[104:107], v183, v183 op_sel_hi:[0,0,0]
	s_barrier
	s_setprio 0
	s_add_i32 s30, s37, s16
	v_lshl_add_u64 v[166:167], v[166:167], 0, s[82:83]
	s_mov_b32 m0, s30
	ds_read_b128 v[196:199], v187 offset:49152
	ds_read_b128 v[200:203], v187 offset:50176
	ds_read_b128 v[204:207], v187 offset:51200
	ds_read_b128 v[208:211], v187 offset:52224
	ds_read_b128 v[212:215], v187 offset:53248
	ds_read_b128 v[216:219], v187 offset:54272
	ds_read_b128 v[226:229], v187 offset:55296
	ds_read_b128 v[230:233], v187 offset:56320
	global_load_lds_dwordx4 v[166:167], off
	s_add_i32 m0, s30, 0x2000
	s_add_u32 s28, s28, 0x20080
	v_lshl_add_u64 v[166:167], v[176:177], 0, s[82:83]
	s_addc_u32 s29, s29, 0
	s_add_i32 s12, s12, s16
	global_load_lds_dwordx4 v[166:167], off
	v_lshl_add_u64 v[166:167], s[28:29], 0, v[26:27]
	s_mov_b32 m0, s12
	s_nop 0
	global_load_lds_dwordx4 v[166:167], off
	v_lshl_add_u64 v[166:167], s[28:29], 0, v[160:161]
	s_add_i32 m0, s12, 0x2000
	s_nop 0
	global_load_lds_dwordx4 v[166:167], off
	v_lshl_add_u64 v[166:167], v[178:179], 0, s[82:83]
	s_mov_b32 m0, s34
	s_nop 0
	global_load_lds_dwordx4 v[166:167], off
	v_lshl_add_u64 v[166:167], v[180:181], 0, s[82:83]
	s_mov_b32 m0, s35
	s_nop 0
	global_load_lds_dwordx4 v[166:167], off
	s_waitcnt vmcnt(8)
	s_waitcnt lgkmcnt(0)
	s_setprio 1
	s_barrier
	v_mfma_scale_f32_16x16x128_f8f6f4 v[76:79], v[10:17], v[196:203], v[76:79], v183, v183 op_sel_hi:[0,0,0]
	v_mfma_scale_f32_16x16x128_f8f6f4 v[80:83], v[188:195], v[196:203], v[80:83], v183, v183 op_sel_hi:[0,0,0]
	v_mfma_scale_f32_16x16x128_f8f6f4 v[60:63], v[10:17], v[204:211], v[60:63], v183, v183 op_sel_hi:[0,0,0]
	v_mfma_scale_f32_16x16x128_f8f6f4 v[64:67], v[188:195], v[204:211], v[64:67], v183, v183 op_sel_hi:[0,0,0]
	v_mfma_scale_f32_16x16x128_f8f6f4 v[44:47], v[10:17], v[212:219], v[44:47], v183, v183 op_sel_hi:[0,0,0]
	v_mfma_scale_f32_16x16x128_f8f6f4 v[48:51], v[188:195], v[212:219], v[48:51], v183, v183 op_sel_hi:[0,0,0]
	v_mfma_scale_f32_16x16x128_f8f6f4 v[28:31], v[10:17], v[226:233], v[28:31], v183, v183 op_sel_hi:[0,0,0]
	v_mfma_scale_f32_16x16x128_f8f6f4 v[32:35], v[188:195], v[226:233], v[32:35], v183, v183 op_sel_hi:[0,0,0]
	s_setprio 0
	s_setprio 1
	v_mfma_scale_f32_16x16x128_f8f6f4 v[84:87], v[2:9], v[196:203], v[84:87], v183, v183 op_sel_hi:[0,0,0]
	v_mfma_scale_f32_16x16x128_f8f6f4 v[88:91], v[18:25], v[196:203], v[88:91], v183, v183 op_sel_hi:[0,0,0]
	v_mfma_scale_f32_16x16x128_f8f6f4 v[68:71], v[2:9], v[204:211], v[68:71], v183, v183 op_sel_hi:[0,0,0]
	v_mfma_scale_f32_16x16x128_f8f6f4 v[72:75], v[18:25], v[204:211], v[72:75], v183, v183 op_sel_hi:[0,0,0]
	v_mfma_scale_f32_16x16x128_f8f6f4 v[52:55], v[2:9], v[212:219], v[52:55], v183, v183 op_sel_hi:[0,0,0]
	v_mfma_scale_f32_16x16x128_f8f6f4 v[56:59], v[18:25], v[212:219], v[56:59], v183, v183 op_sel_hi:[0,0,0]
	v_mfma_scale_f32_16x16x128_f8f6f4 v[40:43], v[2:9], v[226:233], v[40:43], v183, v183 op_sel_hi:[0,0,0]
	v_mfma_scale_f32_16x16x128_f8f6f4 v[36:39], v[18:25], v[226:233], v[36:39], v183, v183 op_sel_hi:[0,0,0]
	s_barrier
	s_setprio 0
	s_add_i32 s36, s36, 2
	s_add_u32 s20, s20, 0x100
	s_addc_u32 s21, s21, 0
	s_cmp_gt_u32 s36, 5
	s_cbranch_scc0 .LBB0_492
	s_cmpk_lt_u32 s8, 0x100
	s_cbranch_scc0 .LBB0_495
	s_barrier

.LBB0_548:
	s_add_u32 s12, s54, 0xffea0080
	s_addc_u32 s58, s55, -1
	s_add_i32 s72, 0, 0x10000
	s_cmp_eq_u32 s80, 4
	s_cselect_b32 s61, s41, s58
	s_cselect_b32 s60, s40, s12
	v_add_u32_e32 v26, s72, v227
	s_cselect_b32 s59, s53, s57
	s_cselect_b32 s58, s52, s1
	s_add_i32 s12, 0, 0x14000
	ds_read_b128 v[146:149], v26
	ds_read_b128 v[150:153], v26 offset:1024
	ds_read_b128 v[154:157], v26 offset:2048
	ds_read_b128 v[158:161], v26 offset:3072
	v_add_u32_e32 v26, s12, v227
	ds_read_b128 v[162:165], v26
	ds_read_b128 v[176:179], v26 offset:1024
	ds_read_b128 v[180:183], v26 offset:2048
	ds_read_b128 v[184:187], v26 offset:3072
	v_lshl_add_u64 v[166:167], s[54:55], 0, v[142:143]
	s_add_i32 m0, s16, 0xc000
	ds_read_b128 v[188:191], v229
	ds_read_b128 v[192:195], v229 offset:1024
	ds_read_b128 v[196:199], v229 offset:2048
	ds_read_b128 v[200:203], v229 offset:3072
	ds_read_b128 v[204:207], v229 offset:4096
	ds_read_b128 v[208:211], v229 offset:5120
	ds_read_b128 v[212:215], v229 offset:6144
	ds_read_b128 v[216:219], v229 offset:7168
	global_load_lds_dwordx4 v[166:167], off
	v_lshl_add_u64 v[166:167], s[54:55], 0, v[144:145]
	s_add_i32 m0, s16, 0xe000
	s_nop 0
	global_load_lds_dwordx4 v[166:167], off
	s_waitcnt vmcnt(8)
	s_waitcnt lgkmcnt(0)
	s_setprio 1
	s_barrier
	v_mfma_f32_16x16x32_bf16 v[2:5], v[146:149], v[188:191], v[2:5]
	v_mfma_f32_16x16x32_bf16 v[6:9], v[154:157], v[188:191], v[6:9]
	v_mfma_f32_16x16x32_bf16 v[10:13], v[146:149], v[196:199], v[10:13]
	v_mfma_f32_16x16x32_bf16 v[14:17], v[154:157], v[196:199], v[14:17]
	v_mfma_f32_16x16x32_bf16 v[18:21], v[146:149], v[204:207], v[18:21]
	v_mfma_f32_16x16x32_bf16 v[22:25], v[154:157], v[204:207], v[22:25]
	v_mfma_f32_16x16x32_bf16 v[28:31], v[146:149], v[212:215], v[28:31]
	v_mfma_f32_16x16x32_bf16 v[32:35], v[154:157], v[212:215], v[32:35]
	v_mfma_f32_16x16x32_bf16 v[2:5], v[150:153], v[192:195], v[2:5]
	v_mfma_f32_16x16x32_bf16 v[6:9], v[158:161], v[192:195], v[6:9]
	v_mfma_f32_16x16x32_bf16 v[10:13], v[150:153], v[200:203], v[10:13]
	v_mfma_f32_16x16x32_bf16 v[14:17], v[158:161], v[200:203], v[14:17]
	v_mfma_f32_16x16x32_bf16 v[18:21], v[150:153], v[208:211], v[18:21]
	v_mfma_f32_16x16x32_bf16 v[22:25], v[158:161], v[208:211], v[22:25]
	v_mfma_f32_16x16x32_bf16 v[28:31], v[150:153], v[216:219], v[28:31]
	v_mfma_f32_16x16x32_bf16 v[32:35], v[158:161], v[216:219], v[32:35]
	s_setprio 0
	s_setprio 1
	v_mfma_f32_16x16x32_bf16 v[36:39], v[162:165], v[188:191], v[36:39]
	v_mfma_f32_16x16x32_bf16 v[40:43], v[180:183], v[188:191], v[40:43]
	v_mfma_f32_16x16x32_bf16 v[44:47], v[162:165], v[196:199], v[44:47]
	v_mfma_f32_16x16x32_bf16 v[48:51], v[180:183], v[196:199], v[48:51]
	v_mfma_f32_16x16x32_bf16 v[52:55], v[162:165], v[204:207], v[52:55]
	v_mfma_f32_16x16x32_bf16 v[56:59], v[180:183], v[204:207], v[56:59]
	v_mfma_f32_16x16x32_bf16 v[60:63], v[162:165], v[212:215], v[60:63]
	v_mfma_f32_16x16x32_bf16 v[64:67], v[180:183], v[212:215], v[64:67]
	v_mfma_f32_16x16x32_bf16 v[36:39], v[176:179], v[192:195], v[36:39]
	v_mfma_f32_16x16x32_bf16 v[40:43], v[184:187], v[192:195], v[40:43]
	v_mfma_f32_16x16x32_bf16 v[44:47], v[176:179], v[200:203], v[44:47]
	v_mfma_f32_16x16x32_bf16 v[48:51], v[184:187], v[200:203], v[48:51]
	v_mfma_f32_16x16x32_bf16 v[52:55], v[176:179], v[208:211], v[52:55]
	v_mfma_f32_16x16x32_bf16 v[56:59], v[184:187], v[208:211], v[56:59]
	v_mfma_f32_16x16x32_bf16 v[60:63], v[176:179], v[216:219], v[60:63]
	v_mfma_f32_16x16x32_bf16 v[64:67], v[184:187], v[216:219], v[64:67]
	s_barrier
	s_setprio 0
	s_add_i32 s72, s72, s15
	v_lshl_add_u64 v[166:167], s[58:59], 0, v[134:135]
	s_mov_b32 m0, s72
	ds_read_b128 v[188:191], v229 offset:16384
	ds_read_b128 v[192:195], v229 offset:17408
	ds_read_b128 v[196:199], v229 offset:18432
	ds_read_b128 v[200:203], v229 offset:19456
	ds_read_b128 v[204:207], v229 offset:20480
	ds_read_b128 v[208:211], v229 offset:21504
	ds_read_b128 v[212:215], v229 offset:22528
	ds_read_b128 v[216:219], v229 offset:23552
	global_load_lds_dwordx4 v[166:167], off
	s_add_i32 m0, s72, 0x2000
	s_add_u32 s72, s58, 0x60000
	v_lshl_add_u64 v[220:221], s[58:59], 0, v[138:139]
	s_addc_u32 s73, s59, 0
	s_add_i32 s12, s12, s15
	global_load_lds_dwordx4 v[220:221], off
	v_lshl_add_u64 v[230:231], s[72:73], 0, v[134:135]
	s_mov_b32 m0, s12
	v_lshl_add_u64 v[232:233], s[60:61], 0, v[136:137]
	global_load_lds_dwordx4 v[230:231], off
	v_lshl_add_u64 v[230:231], s[72:73], 0, v[138:139]
	s_add_i32 m0, s12, 0x2000
	s_nop 0
	global_load_lds_dwordx4 v[230:231], off
	v_lshl_add_u64 v[230:231], s[60:61], 0, v[132:133]
	s_mov_b32 m0, s16
	s_nop 0
	global_load_lds_dwordx4 v[230:231], off
	s_mov_b32 m0, s17
	s_nop 0
	global_load_lds_dwordx4 v[232:233], off
	s_waitcnt vmcnt(8)
	s_waitcnt lgkmcnt(0)
	s_setprio 1
	s_barrier
	v_mfma_f32_16x16x32_bf16 v[68:71], v[146:149], v[188:191], v[68:71]
	v_mfma_f32_16x16x32_bf16 v[72:75], v[154:157], v[188:191], v[72:75]
	v_mfma_f32_16x16x32_bf16 v[76:79], v[146:149], v[196:199], v[76:79]
	v_mfma_f32_16x16x32_bf16 v[80:83], v[154:157], v[196:199], v[80:83]
	v_mfma_f32_16x16x32_bf16 v[84:87], v[146:149], v[204:207], v[84:87]
	v_mfma_f32_16x16x32_bf16 v[88:91], v[154:157], v[204:207], v[88:91]
	v_mfma_f32_16x16x32_bf16 v[92:95], v[146:149], v[212:215], v[92:95]
	v_mfma_f32_16x16x32_bf16 v[96:99], v[154:157], v[212:215], v[96:99]
	v_mfma_f32_16x16x32_bf16 v[68:71], v[150:153], v[192:195], v[68:71]
	v_mfma_f32_16x16x32_bf16 v[72:75], v[158:161], v[192:195], v[72:75]
	v_mfma_f32_16x16x32_bf16 v[76:79], v[150:153], v[200:203], v[76:79]
	v_mfma_f32_16x16x32_bf16 v[80:83], v[158:161], v[200:203], v[80:83]
	v_mfma_f32_16x16x32_bf16 v[84:87], v[150:153], v[208:211], v[84:87]
	v_mfma_f32_16x16x32_bf16 v[88:91], v[158:161], v[208:211], v[88:91]
	v_mfma_f32_16x16x32_bf16 v[92:95], v[150:153], v[216:219], v[92:95]
	v_mfma_f32_16x16x32_bf16 v[96:99], v[158:161], v[216:219], v[96:99]
	s_setprio 0
	s_setprio 1
	v_mfma_f32_16x16x32_bf16 v[100:103], v[162:165], v[188:191], v[100:103]
	v_mfma_f32_16x16x32_bf16 v[104:107], v[180:183], v[188:191], v[104:107]
	v_mfma_f32_16x16x32_bf16 v[108:111], v[162:165], v[196:199], v[108:111]
	v_mfma_f32_16x16x32_bf16 v[112:115], v[180:183], v[196:199], v[112:115]
	v_mfma_f32_16x16x32_bf16 v[116:119], v[162:165], v[204:207], v[116:119]
	v_mfma_f32_16x16x32_bf16 v[120:123], v[180:183], v[204:207], v[120:123]
	v_mfma_f32_16x16x32_bf16 v[124:127], v[162:165], v[212:215], v[124:127]
	v_mfma_f32_16x16x32_bf16 v[128:131], v[180:183], v[212:215], v[128:131]
	v_mfma_f32_16x16x32_bf16 v[100:103], v[176:179], v[192:195], v[100:103]
	v_mfma_f32_16x16x32_bf16 v[104:107], v[184:187], v[192:195], v[104:107]
	v_mfma_f32_16x16x32_bf16 v[108:111], v[176:179], v[200:203], v[108:111]
	v_mfma_f32_16x16x32_bf16 v[112:115], v[184:187], v[200:203], v[112:115]
	v_mfma_f32_16x16x32_bf16 v[116:119], v[176:179], v[208:211], v[116:119]
	v_mfma_f32_16x16x32_bf16 v[120:123], v[184:187], v[208:211], v[120:123]
	v_mfma_f32_16x16x32_bf16 v[124:127], v[176:179], v[216:219], v[124:127]
	v_mfma_f32_16x16x32_bf16 v[128:131], v[184:187], v[216:219], v[128:131]
	s_barrier
	s_setprio 0
	s_add_i32 s12, 0, 0x18000
	v_add_u32_e32 v26, s12, v227
	s_add_i32 s72, 0, 0x1c000
	ds_read_b128 v[146:149], v26
	ds_read_b128 v[150:153], v26 offset:1024
	ds_read_b128 v[154:157], v26 offset:2048
	ds_read_b128 v[158:161], v26 offset:3072
	v_add_u32_e32 v26, s72, v227
	ds_read_b128 v[162:165], v26
	ds_read_b128 v[176:179], v26 offset:1024
	ds_read_b128 v[180:183], v26 offset:2048
	ds_read_b128 v[184:187], v26 offset:3072
	s_add_u32 s60, s60, 0x160000
	s_addc_u32 s61, s61, 0
	s_mov_b32 m0, s22
	v_lshl_add_u64 v[234:235], s[60:61], 0, v[132:133]
	ds_read_b128 v[188:191], v229 offset:32768
	ds_read_b128 v[192:195], v229 offset:33792
	ds_read_b128 v[196:199], v229 offset:34816
	ds_read_b128 v[200:203], v229 offset:35840
	ds_read_b128 v[204:207], v229 offset:36864
	ds_read_b128 v[208:211], v229 offset:37888
	ds_read_b128 v[212:215], v229 offset:38912
	ds_read_b128 v[216:219], v229 offset:39936
	global_load_lds_dwordx4 v[234:235], off
	v_lshl_add_u64 v[234:235], s[60:61], 0, v[136:137]
	s_mov_b32 m0, s23
	s_nop 0
	global_load_lds_dwordx4 v[234:235], off
	s_waitcnt vmcnt(8)
	s_waitcnt lgkmcnt(0)
	s_setprio 1
	s_barrier
	v_mfma_f32_16x16x32_bf16 v[2:5], v[146:149], v[188:191], v[2:5]
	v_mfma_f32_16x16x32_bf16 v[6:9], v[154:157], v[188:191], v[6:9]
	v_mfma_f32_16x16x32_bf16 v[10:13], v[146:149], v[196:199], v[10:13]
	v_mfma_f32_16x16x32_bf16 v[14:17], v[154:157], v[196:199], v[14:17]
	v_mfma_f32_16x16x32_bf16 v[18:21], v[146:149], v[204:207], v[18:21]
	v_mfma_f32_16x16x32_bf16 v[22:25], v[154:157], v[204:207], v[22:25]
	v_mfma_f32_16x16x32_bf16 v[28:31], v[146:149], v[212:215], v[28:31]
	v_mfma_f32_16x16x32_bf16 v[32:35], v[154:157], v[212:215], v[32:35]
	v_mfma_f32_16x16x32_bf16 v[2:5], v[150:153], v[192:195], v[2:5]
	v_mfma_f32_16x16x32_bf16 v[6:9], v[158:161], v[192:195], v[6:9]
	v_mfma_f32_16x16x32_bf16 v[10:13], v[150:153], v[200:203], v[10:13]
	v_mfma_f32_16x16x32_bf16 v[14:17], v[158:161], v[200:203], v[14:17]
	v_mfma_f32_16x16x32_bf16 v[18:21], v[150:153], v[208:211], v[18:21]
	v_mfma_f32_16x16x32_bf16 v[22:25], v[158:161], v[208:211], v[22:25]
	v_mfma_f32_16x16x32_bf16 v[28:31], v[150:153], v[216:219], v[28:31]
	v_mfma_f32_16x16x32_bf16 v[32:35], v[158:161], v[216:219], v[32:35]
	s_setprio 0
	s_setprio 1
	v_mfma_f32_16x16x32_bf16 v[36:39], v[162:165], v[188:191], v[36:39]
	v_mfma_f32_16x16x32_bf16 v[40:43], v[180:183], v[188:191], v[40:43]
	v_mfma_f32_16x16x32_bf16 v[44:47], v[162:165], v[196:199], v[44:47]
	v_mfma_f32_16x16x32_bf16 v[48:51], v[180:183], v[196:199], v[48:51]
	v_mfma_f32_16x16x32_bf16 v[52:55], v[162:165], v[204:207], v[52:55]
	v_mfma_f32_16x16x32_bf16 v[56:59], v[180:183], v[204:207], v[56:59]
	v_mfma_f32_16x16x32_bf16 v[60:63], v[162:165], v[212:215], v[60:63]
	v_mfma_f32_16x16x32_bf16 v[64:67], v[180:183], v[212:215], v[64:67]
	v_mfma_f32_16x16x32_bf16 v[36:39], v[176:179], v[192:195], v[36:39]
	v_mfma_f32_16x16x32_bf16 v[40:43], v[184:187], v[192:195], v[40:43]
	v_mfma_f32_16x16x32_bf16 v[44:47], v[176:179], v[200:203], v[44:47]
	v_mfma_f32_16x16x32_bf16 v[48:51], v[184:187], v[200:203], v[48:51]
	v_mfma_f32_16x16x32_bf16 v[52:55], v[176:179], v[208:211], v[52:55]
	v_mfma_f32_16x16x32_bf16 v[56:59], v[184:187], v[208:211], v[56:59]
	v_mfma_f32_16x16x32_bf16 v[60:63], v[176:179], v[216:219], v[60:63]
	v_mfma_f32_16x16x32_bf16 v[64:67], v[184:187], v[216:219], v[64:67]
	s_barrier
	s_setprio 0
	s_add_i32 s12, s12, s15
	v_lshl_add_u64 v[166:167], v[166:167], 0, s[82:83]
	s_mov_b32 m0, s12
	ds_read_b128 v[188:191], v229 offset:49152
	ds_read_b128 v[192:195], v229 offset:50176
	ds_read_b128 v[196:199], v229 offset:51200
	ds_read_b128 v[200:203], v229 offset:52224
	ds_read_b128 v[204:207], v229 offset:53248
	ds_read_b128 v[208:211], v229 offset:54272
	ds_read_b128 v[212:215], v229 offset:55296
	ds_read_b128 v[216:219], v229 offset:56320
	global_load_lds_dwordx4 v[166:167], off
	s_add_i32 m0, s12, 0x2000
	s_add_u32 s58, s58, 0x60080
	v_lshl_add_u64 v[166:167], v[220:221], 0, s[82:83]
	s_addc_u32 s59, s59, 0
	s_add_i32 s12, s72, s15
	global_load_lds_dwordx4 v[166:167], off
	v_lshl_add_u64 v[166:167], s[58:59], 0, v[134:135]
	s_mov_b32 m0, s12
	s_nop 0
	global_load_lds_dwordx4 v[166:167], off
	v_lshl_add_u64 v[166:167], s[58:59], 0, v[138:139]
	s_add_i32 m0, s12, 0x2000
	s_nop 0
	global_load_lds_dwordx4 v[166:167], off
	v_lshl_add_u64 v[166:167], v[230:231], 0, s[82:83]
	s_mov_b32 m0, s26
	s_nop 0
	global_load_lds_dwordx4 v[166:167], off
	v_lshl_add_u64 v[166:167], v[232:233], 0, s[82:83]
	s_mov_b32 m0, s27
	s_nop 0
	global_load_lds_dwordx4 v[166:167], off
	s_waitcnt vmcnt(8)
	s_waitcnt lgkmcnt(0)
	s_setprio 1
	s_barrier
	v_mfma_f32_16x16x32_bf16 v[68:71], v[146:149], v[188:191], v[68:71]
	v_mfma_f32_16x16x32_bf16 v[72:75], v[154:157], v[188:191], v[72:75]
	v_mfma_f32_16x16x32_bf16 v[76:79], v[146:149], v[196:199], v[76:79]
	v_mfma_f32_16x16x32_bf16 v[80:83], v[154:157], v[196:199], v[80:83]
	v_mfma_f32_16x16x32_bf16 v[84:87], v[146:149], v[204:207], v[84:87]
	v_mfma_f32_16x16x32_bf16 v[88:91], v[154:157], v[204:207], v[88:91]
	v_mfma_f32_16x16x32_bf16 v[92:95], v[146:149], v[212:215], v[92:95]
	v_mfma_f32_16x16x32_bf16 v[96:99], v[154:157], v[212:215], v[96:99]
	v_mfma_f32_16x16x32_bf16 v[68:71], v[150:153], v[192:195], v[68:71]
	v_mfma_f32_16x16x32_bf16 v[72:75], v[158:161], v[192:195], v[72:75]
	v_mfma_f32_16x16x32_bf16 v[76:79], v[150:153], v[200:203], v[76:79]
	v_mfma_f32_16x16x32_bf16 v[80:83], v[158:161], v[200:203], v[80:83]
	v_mfma_f32_16x16x32_bf16 v[84:87], v[150:153], v[208:211], v[84:87]
	v_mfma_f32_16x16x32_bf16 v[88:91], v[158:161], v[208:211], v[88:91]
	v_mfma_f32_16x16x32_bf16 v[92:95], v[150:153], v[216:219], v[92:95]
	v_mfma_f32_16x16x32_bf16 v[96:99], v[158:161], v[216:219], v[96:99]
	s_setprio 0
	s_setprio 1
	v_mfma_f32_16x16x32_bf16 v[100:103], v[162:165], v[188:191], v[100:103]
	v_mfma_f32_16x16x32_bf16 v[104:107], v[180:183], v[188:191], v[104:107]
	v_mfma_f32_16x16x32_bf16 v[108:111], v[162:165], v[196:199], v[108:111]
	v_mfma_f32_16x16x32_bf16 v[112:115], v[180:183], v[196:199], v[112:115]
	v_mfma_f32_16x16x32_bf16 v[116:119], v[162:165], v[204:207], v[116:119]
	v_mfma_f32_16x16x32_bf16 v[120:123], v[180:183], v[204:207], v[120:123]
	v_mfma_f32_16x16x32_bf16 v[124:127], v[162:165], v[212:215], v[124:127]
	v_mfma_f32_16x16x32_bf16 v[128:131], v[180:183], v[212:215], v[128:131]
	v_mfma_f32_16x16x32_bf16 v[100:103], v[176:179], v[192:195], v[100:103]
	v_mfma_f32_16x16x32_bf16 v[104:107], v[184:187], v[192:195], v[104:107]
	v_mfma_f32_16x16x32_bf16 v[108:111], v[176:179], v[200:203], v[108:111]
	v_mfma_f32_16x16x32_bf16 v[112:115], v[184:187], v[200:203], v[112:115]
	v_mfma_f32_16x16x32_bf16 v[116:119], v[176:179], v[208:211], v[116:119]
	v_mfma_f32_16x16x32_bf16 v[120:123], v[184:187], v[208:211], v[120:123]
	v_mfma_f32_16x16x32_bf16 v[124:127], v[176:179], v[216:219], v[124:127]
	v_mfma_f32_16x16x32_bf16 v[128:131], v[184:187], v[216:219], v[128:131]
	s_barrier
	s_setprio 0
	s_add_i32 s80, s80, 2
	s_add_u32 s54, s54, 0x100
	s_addc_u32 s55, s55, 0
	s_add_u32 s1, s1, 0x100
	s_addc_u32 s57, s57, 0
	s_cmp_gt_u32 s80, 5
	s_cbranch_scc0 .LBB0_548
	s_and_b64 vcc, exec, s[30:31]
	s_cbranch_vccz .LBB0_551
	s_barrier

.LBB0_678:
	s_add_u32 s12, s86, 0xffea0080
	s_addc_u32 s72, s87, -1
	s_add_i32 s73, 0, 0x10000
	s_cmp_eq_u32 s61, 12
	s_cselect_b32 s77, s89, s72
	s_cselect_b32 s76, s88, s12
	v_add_u32_e32 v26, s73, v202
	s_cselect_b32 s75, s91, s59
	s_cselect_b32 s74, s90, s35
	s_add_i32 s12, 0, 0x14000
	ds_read_b128 v[132:135], v26
	ds_read_b128 v[136:139], v26 offset:1024
	ds_read_b128 v[140:143], v26 offset:2048
	ds_read_b128 v[144:147], v26 offset:3072
	v_add_u32_e32 v26, s12, v202
	ds_read_b128 v[148:151], v26
	ds_read_b128 v[152:155], v26 offset:1024
	ds_read_b128 v[156:159], v26 offset:2048
	ds_read_b128 v[160:163], v26 offset:3072
	v_lshl_add_u64 v[220:221], s[86:87], 0, v[188:189]
	s_add_i32 m0, s11, 0xc000
	ds_read_b128 v[164:167], v185
	ds_read_b128 v[192:195], v185 offset:1024
	ds_read_b128 v[196:199], v185 offset:2048
	ds_read_b128 v[204:207], v185 offset:3072
	ds_read_b128 v[208:211], v185 offset:4096
	ds_read_b128 v[212:215], v185 offset:5120
	ds_read_b128 v[216:219], v185 offset:6144
	ds_read_b128 v[226:229], v185 offset:7168
	global_load_lds_dwordx4 v[220:221], off
	v_lshl_add_u64 v[220:221], s[86:87], 0, v[190:191]
	s_add_i32 m0, s11, 0xe000
	s_nop 0
	global_load_lds_dwordx4 v[220:221], off
	s_waitcnt vmcnt(8)
	s_waitcnt lgkmcnt(0)
	s_setprio 1
	s_barrier
	v_mfma_f32_16x16x32_bf16 v[2:5], v[132:135], v[164:167], v[2:5]
	v_mfma_f32_16x16x32_bf16 v[6:9], v[140:143], v[164:167], v[6:9]
	v_mfma_f32_16x16x32_bf16 v[10:13], v[132:135], v[196:199], v[10:13]
	v_mfma_f32_16x16x32_bf16 v[14:17], v[140:143], v[196:199], v[14:17]
	v_mfma_f32_16x16x32_bf16 v[18:21], v[132:135], v[208:211], v[18:21]
	v_mfma_f32_16x16x32_bf16 v[22:25], v[140:143], v[208:211], v[22:25]
	v_mfma_f32_16x16x32_bf16 v[28:31], v[132:135], v[216:219], v[28:31]
	v_mfma_f32_16x16x32_bf16 v[32:35], v[140:143], v[216:219], v[32:35]
	v_mfma_f32_16x16x32_bf16 v[2:5], v[136:139], v[192:195], v[2:5]
	v_mfma_f32_16x16x32_bf16 v[6:9], v[144:147], v[192:195], v[6:9]
	v_mfma_f32_16x16x32_bf16 v[10:13], v[136:139], v[204:207], v[10:13]
	v_mfma_f32_16x16x32_bf16 v[14:17], v[144:147], v[204:207], v[14:17]
	v_mfma_f32_16x16x32_bf16 v[18:21], v[136:139], v[212:215], v[18:21]
	v_mfma_f32_16x16x32_bf16 v[22:25], v[144:147], v[212:215], v[22:25]
	v_mfma_f32_16x16x32_bf16 v[28:31], v[136:139], v[226:229], v[28:31]
	v_mfma_f32_16x16x32_bf16 v[32:35], v[144:147], v[226:229], v[32:35]
	s_setprio 0
	s_setprio 1
	v_mfma_f32_16x16x32_bf16 v[36:39], v[148:151], v[164:167], v[36:39]
	v_mfma_f32_16x16x32_bf16 v[40:43], v[156:159], v[164:167], v[40:43]
	v_mfma_f32_16x16x32_bf16 v[44:47], v[148:151], v[196:199], v[44:47]
	v_mfma_f32_16x16x32_bf16 v[48:51], v[156:159], v[196:199], v[48:51]
	v_mfma_f32_16x16x32_bf16 v[52:55], v[148:151], v[208:211], v[52:55]
	v_mfma_f32_16x16x32_bf16 v[56:59], v[156:159], v[208:211], v[56:59]
	v_mfma_f32_16x16x32_bf16 v[60:63], v[148:151], v[216:219], v[60:63]
	v_mfma_f32_16x16x32_bf16 v[64:67], v[156:159], v[216:219], v[64:67]
	v_mfma_f32_16x16x32_bf16 v[36:39], v[152:155], v[192:195], v[36:39]
	v_mfma_f32_16x16x32_bf16 v[40:43], v[160:163], v[192:195], v[40:43]
	v_mfma_f32_16x16x32_bf16 v[44:47], v[152:155], v[204:207], v[44:47]
	v_mfma_f32_16x16x32_bf16 v[48:51], v[160:163], v[204:207], v[48:51]
	v_mfma_f32_16x16x32_bf16 v[52:55], v[152:155], v[212:215], v[52:55]
	v_mfma_f32_16x16x32_bf16 v[56:59], v[160:163], v[212:215], v[56:59]
	v_mfma_f32_16x16x32_bf16 v[60:63], v[152:155], v[226:229], v[60:63]
	v_mfma_f32_16x16x32_bf16 v[64:67], v[160:163], v[226:229], v[64:67]
	s_barrier
	s_setprio 0
	s_add_i32 s72, s73, s8
	v_lshl_add_u64 v[220:221], s[74:75], 0, v[178:179]
	s_mov_b32 m0, s72
	ds_read_b128 v[164:167], v185 offset:16384
	ds_read_b128 v[192:195], v185 offset:17408
	ds_read_b128 v[196:199], v185 offset:18432
	ds_read_b128 v[204:207], v185 offset:19456
	ds_read_b128 v[208:211], v185 offset:20480
	ds_read_b128 v[212:215], v185 offset:21504
	ds_read_b128 v[216:219], v185 offset:22528
	ds_read_b128 v[226:229], v185 offset:23552
	global_load_lds_dwordx4 v[220:221], off
	s_add_i32 m0, s72, 0x2000
	s_add_u32 s72, s74, 0x40000
	v_lshl_add_u64 v[230:231], s[74:75], 0, v[182:183]
	s_addc_u32 s73, s75, 0
	s_add_i32 s12, s12, s8
	global_load_lds_dwordx4 v[230:231], off
	v_lshl_add_u64 v[232:233], s[72:73], 0, v[178:179]
	s_mov_b32 m0, s12
	v_lshl_add_u64 v[234:235], s[76:77], 0, v[180:181]
	global_load_lds_dwordx4 v[232:233], off
	v_lshl_add_u64 v[232:233], s[72:73], 0, v[182:183]
	s_add_i32 m0, s12, 0x2000
	s_nop 0
	global_load_lds_dwordx4 v[232:233], off
	v_lshl_add_u64 v[232:233], s[76:77], 0, v[176:177]
	s_mov_b32 m0, s11
	s_nop 0
	global_load_lds_dwordx4 v[232:233], off
	s_mov_b32 m0, s16
	s_nop 0
	global_load_lds_dwordx4 v[234:235], off
	s_waitcnt vmcnt(8)
	s_waitcnt lgkmcnt(0)
	s_setprio 1
	s_barrier
	v_mfma_f32_16x16x32_bf16 v[68:71], v[132:135], v[164:167], v[68:71]
	v_mfma_f32_16x16x32_bf16 v[72:75], v[140:143], v[164:167], v[72:75]
	v_mfma_f32_16x16x32_bf16 v[76:79], v[132:135], v[196:199], v[76:79]
	v_mfma_f32_16x16x32_bf16 v[80:83], v[140:143], v[196:199], v[80:83]
	v_mfma_f32_16x16x32_bf16 v[84:87], v[132:135], v[208:211], v[84:87]
	v_mfma_f32_16x16x32_bf16 v[88:91], v[140:143], v[208:211], v[88:91]
	v_mfma_f32_16x16x32_bf16 v[92:95], v[132:135], v[216:219], v[92:95]
	v_mfma_f32_16x16x32_bf16 v[96:99], v[140:143], v[216:219], v[96:99]
	v_mfma_f32_16x16x32_bf16 v[68:71], v[136:139], v[192:195], v[68:71]
	v_mfma_f32_16x16x32_bf16 v[72:75], v[144:147], v[192:195], v[72:75]
	v_mfma_f32_16x16x32_bf16 v[76:79], v[136:139], v[204:207], v[76:79]
	v_mfma_f32_16x16x32_bf16 v[80:83], v[144:147], v[204:207], v[80:83]
	v_mfma_f32_16x16x32_bf16 v[84:87], v[136:139], v[212:215], v[84:87]
	v_mfma_f32_16x16x32_bf16 v[88:91], v[144:147], v[212:215], v[88:91]
	v_mfma_f32_16x16x32_bf16 v[92:95], v[136:139], v[226:229], v[92:95]
	v_mfma_f32_16x16x32_bf16 v[96:99], v[144:147], v[226:229], v[96:99]
	s_setprio 0
	s_setprio 1
	v_mfma_f32_16x16x32_bf16 v[100:103], v[148:151], v[164:167], v[100:103]
	v_mfma_f32_16x16x32_bf16 v[104:107], v[156:159], v[164:167], v[104:107]
	v_mfma_f32_16x16x32_bf16 v[108:111], v[148:151], v[196:199], v[108:111]
	v_mfma_f32_16x16x32_bf16 v[112:115], v[156:159], v[196:199], v[112:115]
	v_mfma_f32_16x16x32_bf16 v[116:119], v[148:151], v[208:211], v[116:119]
	v_mfma_f32_16x16x32_bf16 v[120:123], v[156:159], v[208:211], v[120:123]
	v_mfma_f32_16x16x32_bf16 v[124:127], v[148:151], v[216:219], v[124:127]
	v_mfma_f32_16x16x32_bf16 v[128:131], v[156:159], v[216:219], v[128:131]
	v_mfma_f32_16x16x32_bf16 v[100:103], v[152:155], v[192:195], v[100:103]
	v_mfma_f32_16x16x32_bf16 v[104:107], v[160:163], v[192:195], v[104:107]
	v_mfma_f32_16x16x32_bf16 v[108:111], v[152:155], v[204:207], v[108:111]
	v_mfma_f32_16x16x32_bf16 v[112:115], v[160:163], v[204:207], v[112:115]
	v_mfma_f32_16x16x32_bf16 v[116:119], v[152:155], v[212:215], v[116:119]
	v_mfma_f32_16x16x32_bf16 v[120:123], v[160:163], v[212:215], v[120:123]
	v_mfma_f32_16x16x32_bf16 v[124:127], v[152:155], v[226:229], v[124:127]
	v_mfma_f32_16x16x32_bf16 v[128:131], v[160:163], v[226:229], v[128:131]
	s_barrier
	s_setprio 0
	s_add_i32 s12, 0, 0x18000
	v_add_u32_e32 v26, s12, v202
	s_add_i32 s78, 0, 0x1c000
	ds_read_b128 v[132:135], v26
	ds_read_b128 v[136:139], v26 offset:1024
	ds_read_b128 v[140:143], v26 offset:2048
	ds_read_b128 v[144:147], v26 offset:3072
	v_add_u32_e32 v26, s78, v202
	ds_read_b128 v[148:151], v26
	ds_read_b128 v[152:155], v26 offset:1024
	ds_read_b128 v[156:159], v26 offset:2048
	ds_read_b128 v[160:163], v26 offset:3072
	s_add_u32 s72, s76, 0x160000
	s_addc_u32 s73, s77, 0
	s_mov_b32 m0, s17
	v_lshl_add_u64 v[236:237], s[72:73], 0, v[176:177]
	ds_read_b128 v[164:167], v185 offset:32768
	ds_read_b128 v[192:195], v185 offset:33792
	ds_read_b128 v[196:199], v185 offset:34816
	ds_read_b128 v[204:207], v185 offset:35840
	ds_read_b128 v[208:211], v185 offset:36864
	ds_read_b128 v[212:215], v185 offset:37888
	ds_read_b128 v[216:219], v185 offset:38912
	ds_read_b128 v[226:229], v185 offset:39936
	global_load_lds_dwordx4 v[236:237], off
	v_lshl_add_u64 v[236:237], s[72:73], 0, v[180:181]
	s_mov_b32 m0, s22
	s_nop 0
	global_load_lds_dwordx4 v[236:237], off
	s_waitcnt vmcnt(8)
	s_waitcnt lgkmcnt(0)
	s_setprio 1
	s_barrier
	v_mfma_f32_16x16x32_bf16 v[2:5], v[132:135], v[164:167], v[2:5]
	v_mfma_f32_16x16x32_bf16 v[6:9], v[140:143], v[164:167], v[6:9]
	v_mfma_f32_16x16x32_bf16 v[10:13], v[132:135], v[196:199], v[10:13]
	v_mfma_f32_16x16x32_bf16 v[14:17], v[140:143], v[196:199], v[14:17]
	v_mfma_f32_16x16x32_bf16 v[18:21], v[132:135], v[208:211], v[18:21]
	v_mfma_f32_16x16x32_bf16 v[22:25], v[140:143], v[208:211], v[22:25]
	v_mfma_f32_16x16x32_bf16 v[28:31], v[132:135], v[216:219], v[28:31]
	v_mfma_f32_16x16x32_bf16 v[32:35], v[140:143], v[216:219], v[32:35]
	v_mfma_f32_16x16x32_bf16 v[2:5], v[136:139], v[192:195], v[2:5]
	v_mfma_f32_16x16x32_bf16 v[6:9], v[144:147], v[192:195], v[6:9]
	v_mfma_f32_16x16x32_bf16 v[10:13], v[136:139], v[204:207], v[10:13]
	v_mfma_f32_16x16x32_bf16 v[14:17], v[144:147], v[204:207], v[14:17]
	v_mfma_f32_16x16x32_bf16 v[18:21], v[136:139], v[212:215], v[18:21]
	v_mfma_f32_16x16x32_bf16 v[22:25], v[144:147], v[212:215], v[22:25]
	v_mfma_f32_16x16x32_bf16 v[28:31], v[136:139], v[226:229], v[28:31]
	v_mfma_f32_16x16x32_bf16 v[32:35], v[144:147], v[226:229], v[32:35]
	s_setprio 0
	s_setprio 1
	v_mfma_f32_16x16x32_bf16 v[36:39], v[148:151], v[164:167], v[36:39]
	v_mfma_f32_16x16x32_bf16 v[40:43], v[156:159], v[164:167], v[40:43]
	v_mfma_f32_16x16x32_bf16 v[44:47], v[148:151], v[196:199], v[44:47]
	v_mfma_f32_16x16x32_bf16 v[48:51], v[156:159], v[196:199], v[48:51]
	v_mfma_f32_16x16x32_bf16 v[52:55], v[148:151], v[208:211], v[52:55]
	v_mfma_f32_16x16x32_bf16 v[56:59], v[156:159], v[208:211], v[56:59]
	v_mfma_f32_16x16x32_bf16 v[60:63], v[148:151], v[216:219], v[60:63]
	v_mfma_f32_16x16x32_bf16 v[64:67], v[156:159], v[216:219], v[64:67]
	v_mfma_f32_16x16x32_bf16 v[36:39], v[152:155], v[192:195], v[36:39]
	v_mfma_f32_16x16x32_bf16 v[40:43], v[160:163], v[192:195], v[40:43]
	v_mfma_f32_16x16x32_bf16 v[44:47], v[152:155], v[204:207], v[44:47]
	v_mfma_f32_16x16x32_bf16 v[48:51], v[160:163], v[204:207], v[48:51]
	v_mfma_f32_16x16x32_bf16 v[52:55], v[152:155], v[212:215], v[52:55]
	v_mfma_f32_16x16x32_bf16 v[56:59], v[160:163], v[212:215], v[56:59]
	v_mfma_f32_16x16x32_bf16 v[60:63], v[152:155], v[226:229], v[60:63]
	v_mfma_f32_16x16x32_bf16 v[64:67], v[160:163], v[226:229], v[64:67]
	s_barrier
	s_setprio 0
	s_add_i32 s12, s12, s8
	v_lshl_add_u64 v[220:221], v[220:221], 0, s[82:83]
	s_mov_b32 m0, s12
	ds_read_b128 v[164:167], v185 offset:49152
	ds_read_b128 v[192:195], v185 offset:50176
	ds_read_b128 v[196:199], v185 offset:51200
	ds_read_b128 v[204:207], v185 offset:52224
	ds_read_b128 v[208:211], v185 offset:53248
	ds_read_b128 v[212:215], v185 offset:54272
	ds_read_b128 v[216:219], v185 offset:55296
	ds_read_b128 v[226:229], v185 offset:56320
	global_load_lds_dwordx4 v[220:221], off
	s_add_i32 m0, s12, 0x2000
	s_add_u32 s72, s74, 0x40080
	v_lshl_add_u64 v[220:221], v[230:231], 0, s[82:83]
	s_addc_u32 s73, s75, 0
	s_add_i32 s12, s78, s8
	global_load_lds_dwordx4 v[220:221], off
	v_lshl_add_u64 v[220:221], s[72:73], 0, v[178:179]
	s_mov_b32 m0, s12
	s_nop 0
	global_load_lds_dwordx4 v[220:221], off
	v_lshl_add_u64 v[220:221], s[72:73], 0, v[182:183]
	s_add_i32 m0, s12, 0x2000
	s_nop 0
	global_load_lds_dwordx4 v[220:221], off
	v_lshl_add_u64 v[220:221], v[232:233], 0, s[82:83]
	s_mov_b32 m0, s46
	s_nop 0
	global_load_lds_dwordx4 v[220:221], off
	v_lshl_add_u64 v[220:221], v[234:235], 0, s[82:83]
	s_mov_b32 m0, s47
	s_nop 0
	global_load_lds_dwordx4 v[220:221], off
	s_waitcnt vmcnt(8)
	s_waitcnt lgkmcnt(0)
	s_setprio 1
	s_barrier
	v_mfma_f32_16x16x32_bf16 v[68:71], v[132:135], v[164:167], v[68:71]
	v_mfma_f32_16x16x32_bf16 v[72:75], v[140:143], v[164:167], v[72:75]
	v_mfma_f32_16x16x32_bf16 v[76:79], v[132:135], v[196:199], v[76:79]
	v_mfma_f32_16x16x32_bf16 v[80:83], v[140:143], v[196:199], v[80:83]
	v_mfma_f32_16x16x32_bf16 v[84:87], v[132:135], v[208:211], v[84:87]
	v_mfma_f32_16x16x32_bf16 v[88:91], v[140:143], v[208:211], v[88:91]
	v_mfma_f32_16x16x32_bf16 v[92:95], v[132:135], v[216:219], v[92:95]
	v_mfma_f32_16x16x32_bf16 v[96:99], v[140:143], v[216:219], v[96:99]
	v_mfma_f32_16x16x32_bf16 v[68:71], v[136:139], v[192:195], v[68:71]
	v_mfma_f32_16x16x32_bf16 v[72:75], v[144:147], v[192:195], v[72:75]
	v_mfma_f32_16x16x32_bf16 v[76:79], v[136:139], v[204:207], v[76:79]
	v_mfma_f32_16x16x32_bf16 v[80:83], v[144:147], v[204:207], v[80:83]
	v_mfma_f32_16x16x32_bf16 v[84:87], v[136:139], v[212:215], v[84:87]
	v_mfma_f32_16x16x32_bf16 v[88:91], v[144:147], v[212:215], v[88:91]
	v_mfma_f32_16x16x32_bf16 v[92:95], v[136:139], v[226:229], v[92:95]
	v_mfma_f32_16x16x32_bf16 v[96:99], v[144:147], v[226:229], v[96:99]
	s_setprio 0
	s_setprio 1
	v_mfma_f32_16x16x32_bf16 v[100:103], v[148:151], v[164:167], v[100:103]
	v_mfma_f32_16x16x32_bf16 v[104:107], v[156:159], v[164:167], v[104:107]
	v_mfma_f32_16x16x32_bf16 v[108:111], v[148:151], v[196:199], v[108:111]
	v_mfma_f32_16x16x32_bf16 v[112:115], v[156:159], v[196:199], v[112:115]
	v_mfma_f32_16x16x32_bf16 v[116:119], v[148:151], v[208:211], v[116:119]
	v_mfma_f32_16x16x32_bf16 v[120:123], v[156:159], v[208:211], v[120:123]
	v_mfma_f32_16x16x32_bf16 v[124:127], v[148:151], v[216:219], v[124:127]
	v_mfma_f32_16x16x32_bf16 v[128:131], v[156:159], v[216:219], v[128:131]
	v_mfma_f32_16x16x32_bf16 v[100:103], v[152:155], v[192:195], v[100:103]
	v_mfma_f32_16x16x32_bf16 v[104:107], v[160:163], v[192:195], v[104:107]
	v_mfma_f32_16x16x32_bf16 v[108:111], v[152:155], v[204:207], v[108:111]
	v_mfma_f32_16x16x32_bf16 v[112:115], v[160:163], v[204:207], v[112:115]
	v_mfma_f32_16x16x32_bf16 v[116:119], v[152:155], v[212:215], v[116:119]
	v_mfma_f32_16x16x32_bf16 v[120:123], v[160:163], v[212:215], v[120:123]
	v_mfma_f32_16x16x32_bf16 v[124:127], v[152:155], v[226:229], v[124:127]
	v_mfma_f32_16x16x32_bf16 v[128:131], v[160:163], v[226:229], v[128:131]
	s_barrier
	s_setprio 0
	s_add_i32 s61, s61, 2
	s_add_u32 s86, s86, 0x100
	s_addc_u32 s87, s87, 0
	s_add_u32 s35, s35, 0x100
	s_addc_u32 s59, s59, 0
	s_cmp_gt_u32 s61, 13
	s_cbranch_scc0 .LBB0_678
	s_and_b64 vcc, exec, s[26:27]
	s_cbranch_vccz .LBB0_681
	s_barrier

.LBB0_737:
	s_add_u32 s12, s60, 0xffea0080
	s_addc_u32 s58, s61, -1
	s_add_i32 s72, 0, 0x10000
	s_cmp_eq_u32 s55, 12
	s_cselect_b32 s77, s75, s58
	s_cselect_b32 s76, s74, s12
	v_add_u32_e32 v26, s72, v165
	s_cselect_b32 s59, s87, s53
	s_cselect_b32 s58, s86, s31
	s_add_i32 s12, 0, 0x14000
	s_waitcnt lgkmcnt(0)
	ds_read_b128 v[132:135], v26
	ds_read_b128 v[136:139], v26 offset:1024
	ds_read_b128 v[140:143], v26 offset:2048
	ds_read_b128 v[156:159], v26 offset:3072
	v_add_u32_e32 v26, s12, v165
	ds_read_b128 v[160:163], v26
	ds_read_b128 v[176:179], v26 offset:1024
	ds_read_b128 v[180:183], v26 offset:2048
	ds_read_b128 v[184:187], v26 offset:3072
	v_lshl_add_u64 v[220:221], s[60:61], 0, v[152:153]
	s_add_i32 m0, s11, 0xc000
	ds_read_b128 v[188:191], v167
	ds_read_b128 v[192:195], v167 offset:1024
	ds_read_b128 v[196:199], v167 offset:2048
	ds_read_b128 v[200:203], v167 offset:3072
	ds_read_b128 v[204:207], v167 offset:4096
	ds_read_b128 v[208:211], v167 offset:5120
	ds_read_b128 v[212:215], v167 offset:6144
	ds_read_b128 v[216:219], v167 offset:7168
	global_load_lds_dwordx4 v[220:221], off
	v_lshl_add_u64 v[220:221], s[60:61], 0, v[154:155]
	s_add_i32 m0, s11, 0xe000
	s_nop 0
	global_load_lds_dwordx4 v[220:221], off
	s_waitcnt vmcnt(8)
	s_waitcnt lgkmcnt(0)
	s_setprio 1
	s_barrier
	v_mfma_f32_16x16x32_bf16 v[2:5], v[132:135], v[188:191], v[2:5]
	v_mfma_f32_16x16x32_bf16 v[6:9], v[140:143], v[188:191], v[6:9]
	v_mfma_f32_16x16x32_bf16 v[10:13], v[132:135], v[196:199], v[10:13]
	v_mfma_f32_16x16x32_bf16 v[14:17], v[140:143], v[196:199], v[14:17]
	v_mfma_f32_16x16x32_bf16 v[18:21], v[132:135], v[204:207], v[18:21]
	v_mfma_f32_16x16x32_bf16 v[22:25], v[140:143], v[204:207], v[22:25]
	v_mfma_f32_16x16x32_bf16 v[28:31], v[132:135], v[212:215], v[28:31]
	v_mfma_f32_16x16x32_bf16 v[32:35], v[140:143], v[212:215], v[32:35]
	v_mfma_f32_16x16x32_bf16 v[2:5], v[136:139], v[192:195], v[2:5]
	v_mfma_f32_16x16x32_bf16 v[6:9], v[156:159], v[192:195], v[6:9]
	v_mfma_f32_16x16x32_bf16 v[10:13], v[136:139], v[200:203], v[10:13]
	v_mfma_f32_16x16x32_bf16 v[14:17], v[156:159], v[200:203], v[14:17]
	v_mfma_f32_16x16x32_bf16 v[18:21], v[136:139], v[208:211], v[18:21]
	v_mfma_f32_16x16x32_bf16 v[22:25], v[156:159], v[208:211], v[22:25]
	v_mfma_f32_16x16x32_bf16 v[28:31], v[136:139], v[216:219], v[28:31]
	v_mfma_f32_16x16x32_bf16 v[32:35], v[156:159], v[216:219], v[32:35]
	s_setprio 0
	s_setprio 1
	v_mfma_f32_16x16x32_bf16 v[36:39], v[160:163], v[188:191], v[36:39]
	v_mfma_f32_16x16x32_bf16 v[40:43], v[180:183], v[188:191], v[40:43]
	v_mfma_f32_16x16x32_bf16 v[44:47], v[160:163], v[196:199], v[44:47]
	v_mfma_f32_16x16x32_bf16 v[48:51], v[180:183], v[196:199], v[48:51]
	v_mfma_f32_16x16x32_bf16 v[52:55], v[160:163], v[204:207], v[52:55]
	v_mfma_f32_16x16x32_bf16 v[56:59], v[180:183], v[204:207], v[56:59]
	v_mfma_f32_16x16x32_bf16 v[60:63], v[160:163], v[212:215], v[60:63]
	v_mfma_f32_16x16x32_bf16 v[64:67], v[180:183], v[212:215], v[64:67]
	v_mfma_f32_16x16x32_bf16 v[36:39], v[176:179], v[192:195], v[36:39]
	v_mfma_f32_16x16x32_bf16 v[40:43], v[184:187], v[192:195], v[40:43]
	v_mfma_f32_16x16x32_bf16 v[44:47], v[176:179], v[200:203], v[44:47]
	v_mfma_f32_16x16x32_bf16 v[48:51], v[184:187], v[200:203], v[48:51]
	v_mfma_f32_16x16x32_bf16 v[52:55], v[176:179], v[208:211], v[52:55]
	v_mfma_f32_16x16x32_bf16 v[56:59], v[184:187], v[208:211], v[56:59]
	v_mfma_f32_16x16x32_bf16 v[60:63], v[176:179], v[216:219], v[60:63]
	v_mfma_f32_16x16x32_bf16 v[64:67], v[184:187], v[216:219], v[64:67]
	s_barrier
	s_setprio 0
	s_add_i32 s72, s72, s8
	v_lshl_add_u64 v[220:221], s[58:59], 0, v[146:147]
	s_mov_b32 m0, s72
	ds_read_b128 v[188:191], v167 offset:16384
	ds_read_b128 v[192:195], v167 offset:17408
	ds_read_b128 v[196:199], v167 offset:18432
	ds_read_b128 v[200:203], v167 offset:19456
	ds_read_b128 v[204:207], v167 offset:20480
	ds_read_b128 v[208:211], v167 offset:21504
	ds_read_b128 v[212:215], v167 offset:22528
	ds_read_b128 v[216:219], v167 offset:23552
	global_load_lds_dwordx4 v[220:221], off
	s_add_i32 m0, s72, 0x2000
	s_add_u32 s72, s58, 0x40000
	v_lshl_add_u64 v[226:227], s[58:59], 0, v[150:151]
	s_addc_u32 s73, s59, 0
	s_add_i32 s12, s12, s8
	global_load_lds_dwordx4 v[226:227], off
	v_lshl_add_u64 v[228:229], s[72:73], 0, v[146:147]
	s_mov_b32 m0, s12
	v_lshl_add_u64 v[230:231], s[76:77], 0, v[148:149]
	global_load_lds_dwordx4 v[228:229], off
	v_lshl_add_u64 v[228:229], s[72:73], 0, v[150:151]
	s_add_i32 m0, s12, 0x2000
	s_nop 0
	global_load_lds_dwordx4 v[228:229], off
	v_lshl_add_u64 v[228:229], s[76:77], 0, v[144:145]
	s_mov_b32 m0, s11
	s_nop 0
	global_load_lds_dwordx4 v[228:229], off
	s_mov_b32 m0, s16
	s_nop 0
	global_load_lds_dwordx4 v[230:231], off
	s_waitcnt vmcnt(8)
	s_waitcnt lgkmcnt(0)
	s_setprio 1
	s_barrier
	v_mfma_f32_16x16x32_bf16 v[68:71], v[132:135], v[188:191], v[68:71]
	v_mfma_f32_16x16x32_bf16 v[72:75], v[140:143], v[188:191], v[72:75]
	v_mfma_f32_16x16x32_bf16 v[76:79], v[132:135], v[196:199], v[76:79]
	v_mfma_f32_16x16x32_bf16 v[80:83], v[140:143], v[196:199], v[80:83]
	v_mfma_f32_16x16x32_bf16 v[84:87], v[132:135], v[204:207], v[84:87]
	v_mfma_f32_16x16x32_bf16 v[88:91], v[140:143], v[204:207], v[88:91]
	v_mfma_f32_16x16x32_bf16 v[92:95], v[132:135], v[212:215], v[92:95]
	v_mfma_f32_16x16x32_bf16 v[96:99], v[140:143], v[212:215], v[96:99]
	v_mfma_f32_16x16x32_bf16 v[68:71], v[136:139], v[192:195], v[68:71]
	v_mfma_f32_16x16x32_bf16 v[72:75], v[156:159], v[192:195], v[72:75]
	v_mfma_f32_16x16x32_bf16 v[76:79], v[136:139], v[200:203], v[76:79]
	v_mfma_f32_16x16x32_bf16 v[80:83], v[156:159], v[200:203], v[80:83]
	v_mfma_f32_16x16x32_bf16 v[84:87], v[136:139], v[208:211], v[84:87]
	v_mfma_f32_16x16x32_bf16 v[88:91], v[156:159], v[208:211], v[88:91]
	v_mfma_f32_16x16x32_bf16 v[92:95], v[136:139], v[216:219], v[92:95]
	v_mfma_f32_16x16x32_bf16 v[96:99], v[156:159], v[216:219], v[96:99]
	s_setprio 0
	s_setprio 1
	v_mfma_f32_16x16x32_bf16 v[100:103], v[160:163], v[188:191], v[100:103]
	v_mfma_f32_16x16x32_bf16 v[104:107], v[180:183], v[188:191], v[104:107]
	v_mfma_f32_16x16x32_bf16 v[108:111], v[160:163], v[196:199], v[108:111]
	v_mfma_f32_16x16x32_bf16 v[112:115], v[180:183], v[196:199], v[112:115]
	v_mfma_f32_16x16x32_bf16 v[116:119], v[160:163], v[204:207], v[116:119]
	v_mfma_f32_16x16x32_bf16 v[120:123], v[180:183], v[204:207], v[120:123]
	v_mfma_f32_16x16x32_bf16 v[124:127], v[160:163], v[212:215], v[124:127]
	v_mfma_f32_16x16x32_bf16 v[128:131], v[180:183], v[212:215], v[128:131]
	v_mfma_f32_16x16x32_bf16 v[100:103], v[176:179], v[192:195], v[100:103]
	v_mfma_f32_16x16x32_bf16 v[104:107], v[184:187], v[192:195], v[104:107]
	v_mfma_f32_16x16x32_bf16 v[108:111], v[176:179], v[200:203], v[108:111]
	v_mfma_f32_16x16x32_bf16 v[112:115], v[184:187], v[200:203], v[112:115]
	v_mfma_f32_16x16x32_bf16 v[116:119], v[176:179], v[208:211], v[116:119]
	v_mfma_f32_16x16x32_bf16 v[120:123], v[184:187], v[208:211], v[120:123]
	v_mfma_f32_16x16x32_bf16 v[124:127], v[176:179], v[216:219], v[124:127]
	v_mfma_f32_16x16x32_bf16 v[128:131], v[184:187], v[216:219], v[128:131]
	s_barrier
	s_setprio 0
	s_add_i32 s12, 0, 0x18000
	v_add_u32_e32 v26, s12, v165
	s_add_i32 s79, 0, 0x1c000
	ds_read_b128 v[132:135], v26
	ds_read_b128 v[136:139], v26 offset:1024
	ds_read_b128 v[140:143], v26 offset:2048
	ds_read_b128 v[156:159], v26 offset:3072
	v_add_u32_e32 v26, s79, v165
	ds_read_b128 v[160:163], v26
	ds_read_b128 v[176:179], v26 offset:1024
	ds_read_b128 v[180:183], v26 offset:2048
	ds_read_b128 v[184:187], v26 offset:3072
	s_add_u32 s72, s76, 0x160000
	s_addc_u32 s73, s77, 0
	s_mov_b32 m0, s17
	v_lshl_add_u64 v[232:233], s[72:73], 0, v[144:145]
	ds_read_b128 v[188:191], v167 offset:32768
	ds_read_b128 v[192:195], v167 offset:33792
	ds_read_b128 v[196:199], v167 offset:34816
	ds_read_b128 v[200:203], v167 offset:35840
	ds_read_b128 v[204:207], v167 offset:36864
	ds_read_b128 v[208:211], v167 offset:37888
	ds_read_b128 v[212:215], v167 offset:38912
	ds_read_b128 v[216:219], v167 offset:39936
	global_load_lds_dwordx4 v[232:233], off
	v_lshl_add_u64 v[232:233], s[72:73], 0, v[148:149]
	s_mov_b32 m0, s22
	s_nop 0
	global_load_lds_dwordx4 v[232:233], off
	s_waitcnt vmcnt(8)
	s_waitcnt lgkmcnt(0)
	s_setprio 1
	s_barrier
	v_mfma_f32_16x16x32_bf16 v[2:5], v[132:135], v[188:191], v[2:5]
	v_mfma_f32_16x16x32_bf16 v[6:9], v[140:143], v[188:191], v[6:9]
	v_mfma_f32_16x16x32_bf16 v[10:13], v[132:135], v[196:199], v[10:13]
	v_mfma_f32_16x16x32_bf16 v[14:17], v[140:143], v[196:199], v[14:17]
	v_mfma_f32_16x16x32_bf16 v[18:21], v[132:135], v[204:207], v[18:21]
	v_mfma_f32_16x16x32_bf16 v[22:25], v[140:143], v[204:207], v[22:25]
	v_mfma_f32_16x16x32_bf16 v[28:31], v[132:135], v[212:215], v[28:31]
	v_mfma_f32_16x16x32_bf16 v[32:35], v[140:143], v[212:215], v[32:35]
	v_mfma_f32_16x16x32_bf16 v[2:5], v[136:139], v[192:195], v[2:5]
	v_mfma_f32_16x16x32_bf16 v[6:9], v[156:159], v[192:195], v[6:9]
	v_mfma_f32_16x16x32_bf16 v[10:13], v[136:139], v[200:203], v[10:13]
	v_mfma_f32_16x16x32_bf16 v[14:17], v[156:159], v[200:203], v[14:17]
	v_mfma_f32_16x16x32_bf16 v[18:21], v[136:139], v[208:211], v[18:21]
	v_mfma_f32_16x16x32_bf16 v[22:25], v[156:159], v[208:211], v[22:25]
	v_mfma_f32_16x16x32_bf16 v[28:31], v[136:139], v[216:219], v[28:31]
	v_mfma_f32_16x16x32_bf16 v[32:35], v[156:159], v[216:219], v[32:35]
	s_setprio 0
	s_setprio 1
	v_mfma_f32_16x16x32_bf16 v[36:39], v[160:163], v[188:191], v[36:39]
	v_mfma_f32_16x16x32_bf16 v[40:43], v[180:183], v[188:191], v[40:43]
	v_mfma_f32_16x16x32_bf16 v[44:47], v[160:163], v[196:199], v[44:47]
	v_mfma_f32_16x16x32_bf16 v[48:51], v[180:183], v[196:199], v[48:51]
	v_mfma_f32_16x16x32_bf16 v[52:55], v[160:163], v[204:207], v[52:55]
	v_mfma_f32_16x16x32_bf16 v[56:59], v[180:183], v[204:207], v[56:59]
	v_mfma_f32_16x16x32_bf16 v[60:63], v[160:163], v[212:215], v[60:63]
	v_mfma_f32_16x16x32_bf16 v[64:67], v[180:183], v[212:215], v[64:67]
	v_mfma_f32_16x16x32_bf16 v[36:39], v[176:179], v[192:195], v[36:39]
	v_mfma_f32_16x16x32_bf16 v[40:43], v[184:187], v[192:195], v[40:43]
	v_mfma_f32_16x16x32_bf16 v[44:47], v[176:179], v[200:203], v[44:47]
	v_mfma_f32_16x16x32_bf16 v[48:51], v[184:187], v[200:203], v[48:51]
	v_mfma_f32_16x16x32_bf16 v[52:55], v[176:179], v[208:211], v[52:55]
	v_mfma_f32_16x16x32_bf16 v[56:59], v[184:187], v[208:211], v[56:59]
	v_mfma_f32_16x16x32_bf16 v[60:63], v[176:179], v[216:219], v[60:63]
	v_mfma_f32_16x16x32_bf16 v[64:67], v[184:187], v[216:219], v[64:67]
	s_barrier
	s_setprio 0
	s_add_i32 s12, s12, s8
	v_lshl_add_u64 v[220:221], v[220:221], 0, s[82:83]
	s_mov_b32 m0, s12
	ds_read_b128 v[188:191], v167 offset:49152
	ds_read_b128 v[192:195], v167 offset:50176
	ds_read_b128 v[196:199], v167 offset:51200
	ds_read_b128 v[200:203], v167 offset:52224
	ds_read_b128 v[204:207], v167 offset:53248
	ds_read_b128 v[208:211], v167 offset:54272
	ds_read_b128 v[212:215], v167 offset:55296
	ds_read_b128 v[216:219], v167 offset:56320
	global_load_lds_dwordx4 v[220:221], off
	s_add_i32 m0, s12, 0x2000
	s_add_u32 s58, s58, 0x40080
	v_lshl_add_u64 v[220:221], v[226:227], 0, s[82:83]
	s_addc_u32 s59, s59, 0
	s_add_i32 s12, s79, s8
	global_load_lds_dwordx4 v[220:221], off
	v_lshl_add_u64 v[220:221], s[58:59], 0, v[146:147]
	s_mov_b32 m0, s12
	s_nop 0
	global_load_lds_dwordx4 v[220:221], off
	v_lshl_add_u64 v[220:221], s[58:59], 0, v[150:151]
	s_add_i32 m0, s12, 0x2000
	s_nop 0
	global_load_lds_dwordx4 v[220:221], off
	v_lshl_add_u64 v[220:221], v[228:229], 0, s[82:83]
	s_mov_b32 m0, s46
	s_nop 0
	global_load_lds_dwordx4 v[220:221], off
	v_lshl_add_u64 v[220:221], v[230:231], 0, s[82:83]
	s_mov_b32 m0, s47
	s_nop 0
	global_load_lds_dwordx4 v[220:221], off
	s_waitcnt vmcnt(8)
	s_waitcnt lgkmcnt(0)
	s_setprio 1
	s_barrier
	v_mfma_f32_16x16x32_bf16 v[68:71], v[132:135], v[188:191], v[68:71]
	v_mfma_f32_16x16x32_bf16 v[72:75], v[140:143], v[188:191], v[72:75]
	v_mfma_f32_16x16x32_bf16 v[76:79], v[132:135], v[196:199], v[76:79]
	v_mfma_f32_16x16x32_bf16 v[80:83], v[140:143], v[196:199], v[80:83]
	v_mfma_f32_16x16x32_bf16 v[84:87], v[132:135], v[204:207], v[84:87]
	v_mfma_f32_16x16x32_bf16 v[88:91], v[140:143], v[204:207], v[88:91]
	v_mfma_f32_16x16x32_bf16 v[92:95], v[132:135], v[212:215], v[92:95]
	v_mfma_f32_16x16x32_bf16 v[96:99], v[140:143], v[212:215], v[96:99]
	v_mfma_f32_16x16x32_bf16 v[68:71], v[136:139], v[192:195], v[68:71]
	v_mfma_f32_16x16x32_bf16 v[72:75], v[156:159], v[192:195], v[72:75]
	v_mfma_f32_16x16x32_bf16 v[76:79], v[136:139], v[200:203], v[76:79]
	v_mfma_f32_16x16x32_bf16 v[80:83], v[156:159], v[200:203], v[80:83]
	v_mfma_f32_16x16x32_bf16 v[84:87], v[136:139], v[208:211], v[84:87]
	v_mfma_f32_16x16x32_bf16 v[88:91], v[156:159], v[208:211], v[88:91]
	v_mfma_f32_16x16x32_bf16 v[92:95], v[136:139], v[216:219], v[92:95]
	v_mfma_f32_16x16x32_bf16 v[96:99], v[156:159], v[216:219], v[96:99]
	s_setprio 0
	s_setprio 1
	v_mfma_f32_16x16x32_bf16 v[100:103], v[160:163], v[188:191], v[100:103]
	v_mfma_f32_16x16x32_bf16 v[104:107], v[180:183], v[188:191], v[104:107]
	v_mfma_f32_16x16x32_bf16 v[108:111], v[160:163], v[196:199], v[108:111]
	v_mfma_f32_16x16x32_bf16 v[112:115], v[180:183], v[196:199], v[112:115]
	v_mfma_f32_16x16x32_bf16 v[116:119], v[160:163], v[204:207], v[116:119]
	v_mfma_f32_16x16x32_bf16 v[120:123], v[180:183], v[204:207], v[120:123]
	v_mfma_f32_16x16x32_bf16 v[124:127], v[160:163], v[212:215], v[124:127]
	v_mfma_f32_16x16x32_bf16 v[128:131], v[180:183], v[212:215], v[128:131]
	v_mfma_f32_16x16x32_bf16 v[100:103], v[176:179], v[192:195], v[100:103]
	v_mfma_f32_16x16x32_bf16 v[104:107], v[184:187], v[192:195], v[104:107]
	v_mfma_f32_16x16x32_bf16 v[108:111], v[176:179], v[200:203], v[108:111]
	v_mfma_f32_16x16x32_bf16 v[112:115], v[184:187], v[200:203], v[112:115]
	v_mfma_f32_16x16x32_bf16 v[116:119], v[176:179], v[208:211], v[116:119]
	v_mfma_f32_16x16x32_bf16 v[120:123], v[184:187], v[208:211], v[120:123]
	v_mfma_f32_16x16x32_bf16 v[124:127], v[176:179], v[216:219], v[124:127]
	v_mfma_f32_16x16x32_bf16 v[128:131], v[184:187], v[216:219], v[128:131]
	s_barrier
	s_setprio 0
	s_add_i32 s55, s55, 2
	s_add_u32 s60, s60, 0x100
	s_addc_u32 s61, s61, 0
	s_add_u32 s31, s31, 0x100
	s_addc_u32 s53, s53, 0
	s_cmp_gt_u32 s55, 13
	s_cbranch_scc0 .LBB0_737
	s_and_b64 vcc, exec, s[26:27]
	s_cbranch_vccz .LBB0_740
	s_barrier
